# all other GEMM K-loops: LDS-DMA pieces with loop-invariant lane offsets use the SGPR-base addressing form (no 64-bit VALU add per piece)
# speedup vs baseline: 1.0016x; 1.0016x over previous
; #define PG8_STAGE(bufoff, gbase, voff) do { _Pragma("unroll") for (int _i = 0; _i < 2; ++_i) \
;         __builtin_amdgcn_global_load_lds((const unsigned*)((const char*)(gbase) + (voff)[_i]), (LAS unsigned*)(lds + (bufoff) + ldsw + _i * 8192), 16, 0, 0); } while (0)
; #define PG8_LDA(dst, b, h) do { _Pragma("unroll") for (int m = 0; m < NM; ++m) _Pragma("unroll") for (int k = 0; k < 2; ++k) dst[m][k] = *(const LAS bf16x8*)(lds + PG8_SA(b, h) + aoff + m * 2048 + k * 1024); } while (0)
; #define PG8_LDB(dst, b, h) do { _Pragma("unroll") for (int n = 0; n < 2; ++n) _Pragma("unroll") for (int k = 0; k < 2; ++k) dst[n][k] = *(const LAS bf16x8*)(lds + PG8_SB(b, h) + boff + n * 2048 + k * 1024); } while (0)
; #define PG8_MMA(ai, bj, At, Bt) do { __builtin_amdgcn_s_setprio(1); _Pragma("unroll") for (int m = 0; m < NM; ++m) _Pragma("unroll") for (int n = 0; n < 2; ++n) _Pragma("unroll") for (int k = 0; k < 2; ++k) \
;         acc[ai][bj][m][n] = __builtin_amdgcn_mfma_f32_16x16x32_bf16(Bt[n][k], At[m][k], acc[ai][bj][m][n], 0, 0, 0); __builtin_amdgcn_s_setprio(0); } while (0)
; #define PG8_WAIT_V(n) asm volatile("s_waitcnt vmcnt(" #n ")" ::: "memory")
; #define PG8_WAIT_L(n) asm volatile("s_waitcnt lgkmcnt(" #n ")" ::: "memory")
; #define PG8_BAR __builtin_amdgcn_s_barrier()
; #define PG8_SCHED __builtin_amdgcn_sched_barrier(0)
;     ...
;         for (int t = 0; t < nt; t += 2) {
;             const bool last = (t == nt - 2);
;             const char* a1 = cA + (size_t)(t + 1) * kstep;
;             const char* a2 = last ? nA : cA + (size_t)(t + 2) * kstep; const char* b2 = last ? nB : cB + (size_t)(t + 2) * kstep;
;             const char* a3 = a2 + kstep; const char* b3 = b2 + kstep;
;             if constexpr (SP2) {
;             PG8_LDB(B0, 0, 0); PG8_LDB(B1, 0, 1); PG8_SCHED; PG8_LDA(At, 0, 0); PG8_STAGE(PG8_SA(1, 1), a1 + hstepA, voffA);
;             PG8_WAIT_V(8); PG8_WAIT_L(0); PG8_BAR; PG8_MMA(0, 0, At, B0); PG8_MMA(0, 1, At, B1); PG8_BAR; PG8_SCHED;
;             PG8_LDA(At, 0, 1); PG8_STAGE(PG8_SB(0, 0), b2, voffB); PG8_STAGE(PG8_SB(0, 1), b2 + hstepB, voffB); PG8_STAGE(PG8_SA(0, 0), a2, voffA);
;             PG8_WAIT_V(8); PG8_WAIT_L(0); PG8_BAR; PG8_MMA(1, 0, At, B0); PG8_MMA(1, 1, At, B1); PG8_BAR; PG8_SCHED;
.LBB0_200:
	ds_read_b128 v[26:29], v172
	ds_read_b128 v[30:33], v172 offset:1024
	ds_read_b128 v[42:45], v172 offset:2048
	ds_read_b128 v[46:49], v172 offset:3072
	ds_read_b128 v[146:149], v173
	ds_read_b128 v[150:153], v173 offset:1024
	ds_read_b128 v[164:167], v173 offset:2048
	ds_read_b128 v[168:171], v173 offset:3072
	s_add_u32 s30, s28, 0xfff80080
	s_addc_u32 s31, s29, -1
	s_cmp_eq_u32 s56, 28
	s_cselect_b32 s35, s2, s31
	s_cselect_b32 s34, s3, s30
	s_cselect_b32 s31, s9, s54
	s_cselect_b32 s30, s21, s23
	s_add_i32 m0, s43, 0xc000
	ds_read_b128 v[178:181], v174
	ds_read_b128 v[182:185], v174 offset:1024
	ds_read_b128 v[186:189], v174 offset:2048
	ds_read_b128 v[190:193], v174 offset:3072
	ds_read_b128 v[194:197], v174 offset:4096
	ds_read_b128 v[198:201], v174 offset:5120
	ds_read_b128 v[202:205], v174 offset:6144
	ds_read_b128 v[206:209], v174 offset:7168
	global_load_lds_dwordx4 v160, s[28:29]
	s_add_i32 m0, s43, 0xe000
	s_nop 0
	global_load_lds_dwordx4 v162, s[28:29]
	s_waitcnt vmcnt(8)
	s_waitcnt lgkmcnt(0)
	s_barrier
	s_setprio 1
	s_waitcnt lgkmcnt(0)
	v_mfma_f32_16x16x32_bf16 v[142:145], v[26:29], v[178:181], v[142:145]
	v_mfma_f32_16x16x32_bf16 v[138:141], v[42:45], v[178:181], v[138:141]
	v_mfma_f32_16x16x32_bf16 v[126:129], v[26:29], v[186:189], v[126:129]
	v_mfma_f32_16x16x32_bf16 v[122:125], v[42:45], v[186:189], v[122:125]
	v_mfma_f32_16x16x32_bf16 v[110:113], v[26:29], v[194:197], v[110:113]
	v_mfma_f32_16x16x32_bf16 v[106:109], v[42:45], v[194:197], v[106:109]
	v_mfma_f32_16x16x32_bf16 v[94:97], v[26:29], v[202:205], v[94:97]
	v_mfma_f32_16x16x32_bf16 v[90:93], v[42:45], v[202:205], v[90:93]
	v_mfma_f32_16x16x32_bf16 v[142:145], v[30:33], v[182:185], v[142:145]
	v_mfma_f32_16x16x32_bf16 v[138:141], v[46:49], v[182:185], v[138:141]
	v_mfma_f32_16x16x32_bf16 v[126:129], v[30:33], v[190:193], v[126:129]
	v_mfma_f32_16x16x32_bf16 v[122:125], v[46:49], v[190:193], v[122:125]
	v_mfma_f32_16x16x32_bf16 v[110:113], v[30:33], v[198:201], v[110:113]
	v_mfma_f32_16x16x32_bf16 v[106:109], v[46:49], v[198:201], v[106:109]
	v_mfma_f32_16x16x32_bf16 v[94:97], v[30:33], v[206:209], v[94:97]
	v_mfma_f32_16x16x32_bf16 v[90:93], v[46:49], v[206:209], v[90:93]
	s_setprio 0
	s_setprio 1
	v_mfma_f32_16x16x32_bf16 v[134:137], v[146:149], v[178:181], v[134:137]
	v_mfma_f32_16x16x32_bf16 v[130:133], v[164:167], v[178:181], v[130:133]
	v_mfma_f32_16x16x32_bf16 v[118:121], v[146:149], v[186:189], v[118:121]
	v_mfma_f32_16x16x32_bf16 v[114:117], v[164:167], v[186:189], v[114:117]
	v_mfma_f32_16x16x32_bf16 v[102:105], v[146:149], v[194:197], v[102:105]
	v_mfma_f32_16x16x32_bf16 v[98:101], v[164:167], v[194:197], v[98:101]
	v_mfma_f32_16x16x32_bf16 v[86:89], v[146:149], v[202:205], v[86:89]
	v_mfma_f32_16x16x32_bf16 v[82:85], v[164:167], v[202:205], v[82:85]
	v_mfma_f32_16x16x32_bf16 v[134:137], v[150:153], v[182:185], v[134:137]
	v_mfma_f32_16x16x32_bf16 v[130:133], v[168:171], v[182:185], v[130:133]
	v_mfma_f32_16x16x32_bf16 v[118:121], v[150:153], v[190:193], v[118:121]
	v_mfma_f32_16x16x32_bf16 v[114:117], v[168:171], v[190:193], v[114:117]
	v_mfma_f32_16x16x32_bf16 v[102:105], v[150:153], v[198:201], v[102:105]
	v_mfma_f32_16x16x32_bf16 v[98:101], v[168:171], v[198:201], v[98:101]
	v_mfma_f32_16x16x32_bf16 v[86:89], v[150:153], v[206:209], v[86:89]
	v_mfma_f32_16x16x32_bf16 v[82:85], v[168:171], v[206:209], v[82:85]
	s_setprio 0
	s_barrier
	s_mov_b32 m0, s39
	v_lshl_add_u64 v[210:211], s[30:31], 0, v[0:1]
	s_add_u32 s72, s30, 0x80000
	ds_read_b128 v[178:181], v174 offset:16384
	ds_read_b128 v[182:185], v174 offset:17408
	ds_read_b128 v[186:189], v174 offset:18432
	ds_read_b128 v[190:193], v174 offset:19456
	ds_read_b128 v[194:197], v174 offset:20480
	ds_read_b128 v[198:201], v174 offset:21504
	ds_read_b128 v[202:205], v174 offset:22528
	ds_read_b128 v[206:209], v174 offset:23552
	global_load_lds_dwordx4 v0, s[30:31]
	v_lshl_add_u64 v[212:213], s[30:31], 0, v[158:159]
	s_mov_b32 m0, s40
	s_addc_u32 s73, s31, 0
	global_load_lds_dwordx4 v158, s[30:31]
	s_mov_b32 m0, s41
	v_lshl_add_u64 v[216:217], s[34:35], 0, v[156:157]
	global_load_lds_dwordx4 v0, s[72:73]
	s_mov_b32 m0, s42
	s_nop 0
	global_load_lds_dwordx4 v158, s[72:73]
	v_lshl_add_u64 v[214:215], s[34:35], 0, v[154:155]
	s_mov_b32 m0, s43
	s_nop 0
	global_load_lds_dwordx4 v154, s[34:35]
	s_mov_b32 m0, s44
	s_nop 0
	global_load_lds_dwordx4 v156, s[34:35]
	s_waitcnt vmcnt(8)
	s_waitcnt lgkmcnt(0)
	s_barrier
	s_setprio 1
	s_waitcnt lgkmcnt(0)
	v_mfma_f32_16x16x32_bf16 v[78:81], v[26:29], v[178:181], v[78:81]
	v_mfma_f32_16x16x32_bf16 v[74:77], v[42:45], v[178:181], v[74:77]
	v_mfma_f32_16x16x32_bf16 v[62:65], v[26:29], v[186:189], v[62:65]
	v_mfma_f32_16x16x32_bf16 v[58:61], v[42:45], v[186:189], v[58:61]
	v_mfma_f32_16x16x32_bf16 v[38:41], v[26:29], v[194:197], v[38:41]
	v_mfma_f32_16x16x32_bf16 v[34:37], v[42:45], v[194:197], v[34:37]
	v_mfma_f32_16x16x32_bf16 v[14:17], v[26:29], v[202:205], v[14:17]
	v_mfma_f32_16x16x32_bf16 v[10:13], v[42:45], v[202:205], v[10:13]
	v_mfma_f32_16x16x32_bf16 v[78:81], v[30:33], v[182:185], v[78:81]
	v_mfma_f32_16x16x32_bf16 v[74:77], v[46:49], v[182:185], v[74:77]
	v_mfma_f32_16x16x32_bf16 v[62:65], v[30:33], v[190:193], v[62:65]
	v_mfma_f32_16x16x32_bf16 v[58:61], v[46:49], v[190:193], v[58:61]
	v_mfma_f32_16x16x32_bf16 v[38:41], v[30:33], v[198:201], v[38:41]
	v_mfma_f32_16x16x32_bf16 v[34:37], v[46:49], v[198:201], v[34:37]
	v_mfma_f32_16x16x32_bf16 v[14:17], v[30:33], v[206:209], v[14:17]
	v_mfma_f32_16x16x32_bf16 v[10:13], v[46:49], v[206:209], v[10:13]
	s_setprio 0
	s_setprio 1
	v_mfma_f32_16x16x32_bf16 v[22:25], v[146:149], v[194:197], v[22:25]
	v_mfma_f32_16x16x32_bf16 v[18:21], v[164:167], v[194:197], v[18:21]
	v_mfma_f32_16x16x32_bf16 v[6:9], v[146:149], v[202:205], v[6:9]
	v_mfma_f32_16x16x32_bf16 v[2:5], v[164:167], v[202:205], v[2:5]
	v_mfma_f32_16x16x32_bf16 v[26:29], v[146:149], v[178:181], v[70:73]
	v_mfma_f32_16x16x32_bf16 v[30:33], v[164:167], v[178:181], v[66:69]
	v_mfma_f32_16x16x32_bf16 v[42:45], v[146:149], v[186:189], v[54:57]
	v_mfma_f32_16x16x32_bf16 v[46:49], v[164:167], v[186:189], v[50:53]
	v_mfma_f32_16x16x32_bf16 v[22:25], v[150:153], v[198:201], v[22:25]
	v_mfma_f32_16x16x32_bf16 v[18:21], v[168:171], v[198:201], v[18:21]
	v_mfma_f32_16x16x32_bf16 v[6:9], v[150:153], v[206:209], v[6:9]
	v_mfma_f32_16x16x32_bf16 v[2:5], v[168:171], v[206:209], v[2:5]
	v_mfma_f32_16x16x32_bf16 v[26:29], v[150:153], v[182:185], v[26:29]
	v_mfma_f32_16x16x32_bf16 v[30:33], v[168:171], v[182:185], v[30:33]
	v_mfma_f32_16x16x32_bf16 v[42:45], v[150:153], v[190:193], v[42:45]
	v_mfma_f32_16x16x32_bf16 v[46:49], v[168:171], v[190:193], v[46:49]
	s_setprio 0
	s_barrier
; #define PG8_STAGE(bufoff, gbase, voff) do { _Pragma("unroll") for (int _i = 0; _i < 2; ++_i) \
;         __builtin_amdgcn_global_load_lds((const unsigned*)((const char*)(gbase) + (voff)[_i]), (LAS unsigned*)(lds + (bufoff) + ldsw + _i * 8192), 16, 0, 0); } while (0)
; #define PG8_LDA(dst, b, h) do { _Pragma("unroll") for (int m = 0; m < NM; ++m) _Pragma("unroll") for (int k = 0; k < 2; ++k) dst[m][k] = *(const LAS bf16x8*)(lds + PG8_SA(b, h) + aoff + m * 2048 + k * 1024); } while (0)
; #define PG8_LDB(dst, b, h) do { _Pragma("unroll") for (int n = 0; n < 2; ++n) _Pragma("unroll") for (int k = 0; k < 2; ++k) dst[n][k] = *(const LAS bf16x8*)(lds + PG8_SB(b, h) + boff + n * 2048 + k * 1024); } while (0)
; #define PG8_MMA(ai, bj, At, Bt) do { __builtin_amdgcn_s_setprio(1); _Pragma("unroll") for (int m = 0; m < NM; ++m) _Pragma("unroll") for (int n = 0; n < 2; ++n) _Pragma("unroll") for (int k = 0; k < 2; ++k) \
;         acc[ai][bj][m][n] = __builtin_amdgcn_mfma_f32_16x16x32_bf16(Bt[n][k], At[m][k], acc[ai][bj][m][n], 0, 0, 0); __builtin_amdgcn_s_setprio(0); } while (0)
; #define PG8_WAIT_V(n) asm volatile("s_waitcnt vmcnt(" #n ")" ::: "memory")
; #define PG8_WAIT_L(n) asm volatile("s_waitcnt lgkmcnt(" #n ")" ::: "memory")
; #define PG8_BAR __builtin_amdgcn_s_barrier()
; #define PG8_SCHED __builtin_amdgcn_sched_barrier(0)
;     ...
;             PG8_LDB(B0, 1, 0); PG8_LDB(B1, 1, 1); PG8_SCHED; PG8_LDA(At, 1, 0); PG8_STAGE(PG8_SA(0, 1), a2 + hstepA, voffA);
;             PG8_WAIT_V(8); PG8_WAIT_L(0); PG8_BAR; PG8_MMA(0, 0, At, B0); PG8_MMA(0, 1, At, B1); PG8_BAR; PG8_SCHED;
;             PG8_LDA(At, 1, 1); PG8_STAGE(PG8_SB(1, 0), b3, voffB); PG8_STAGE(PG8_SB(1, 1), b3 + hstepB, voffB); PG8_STAGE(PG8_SA(1, 0), a3, voffA);
;             PG8_WAIT_V(8); PG8_WAIT_L(0); PG8_BAR; PG8_MMA(1, 0, At, B0); PG8_MMA(1, 1, At, B1); PG8_BAR; PG8_SCHED;
	ds_read_b128 v[50:53], v175
	ds_read_b128 v[54:57], v175 offset:1024
	ds_read_b128 v[66:69], v175 offset:2048
	ds_read_b128 v[70:73], v175 offset:3072
	ds_read_b128 v[146:149], v176
	ds_read_b128 v[150:153], v176 offset:1024
	ds_read_b128 v[164:167], v176 offset:2048
	ds_read_b128 v[168:171], v176 offset:3072
	s_add_u32 s34, s34, 0x80000
	s_addc_u32 s35, s35, 0
	s_mov_b32 m0, s45
	ds_read_b128 v[178:181], v174 offset:32768
	ds_read_b128 v[182:185], v174 offset:33792
	ds_read_b128 v[186:189], v174 offset:34816
	ds_read_b128 v[190:193], v174 offset:35840
	ds_read_b128 v[194:197], v174 offset:36864
	ds_read_b128 v[198:201], v174 offset:37888
	ds_read_b128 v[202:205], v174 offset:38912
	ds_read_b128 v[206:209], v174 offset:39936
	global_load_lds_dwordx4 v154, s[34:35]
	s_mov_b32 m0, s46
	s_nop 0
	global_load_lds_dwordx4 v156, s[34:35]
	s_waitcnt vmcnt(8)
	s_waitcnt lgkmcnt(0)
	s_barrier
	s_setprio 1
	s_waitcnt lgkmcnt(0)
	v_mfma_f32_16x16x32_bf16 v[142:145], v[50:53], v[178:181], v[142:145]
	v_mfma_f32_16x16x32_bf16 v[138:141], v[66:69], v[178:181], v[138:141]
	v_mfma_f32_16x16x32_bf16 v[126:129], v[50:53], v[186:189], v[126:129]
	v_mfma_f32_16x16x32_bf16 v[122:125], v[66:69], v[186:189], v[122:125]
	v_mfma_f32_16x16x32_bf16 v[110:113], v[50:53], v[194:197], v[110:113]
	v_mfma_f32_16x16x32_bf16 v[106:109], v[66:69], v[194:197], v[106:109]
	v_mfma_f32_16x16x32_bf16 v[94:97], v[50:53], v[202:205], v[94:97]
	v_mfma_f32_16x16x32_bf16 v[90:93], v[66:69], v[202:205], v[90:93]
	v_mfma_f32_16x16x32_bf16 v[142:145], v[54:57], v[182:185], v[142:145]
	v_mfma_f32_16x16x32_bf16 v[138:141], v[70:73], v[182:185], v[138:141]
	v_mfma_f32_16x16x32_bf16 v[126:129], v[54:57], v[190:193], v[126:129]
	v_mfma_f32_16x16x32_bf16 v[122:125], v[70:73], v[190:193], v[122:125]
	v_mfma_f32_16x16x32_bf16 v[110:113], v[54:57], v[198:201], v[110:113]
	v_mfma_f32_16x16x32_bf16 v[106:109], v[70:73], v[198:201], v[106:109]
	v_mfma_f32_16x16x32_bf16 v[94:97], v[54:57], v[206:209], v[94:97]
	v_mfma_f32_16x16x32_bf16 v[90:93], v[70:73], v[206:209], v[90:93]
	s_setprio 0
	s_setprio 1
	v_mfma_f32_16x16x32_bf16 v[134:137], v[146:149], v[178:181], v[134:137]
	v_mfma_f32_16x16x32_bf16 v[130:133], v[164:167], v[178:181], v[130:133]
	v_mfma_f32_16x16x32_bf16 v[118:121], v[146:149], v[186:189], v[118:121]
	v_mfma_f32_16x16x32_bf16 v[114:117], v[164:167], v[186:189], v[114:117]
	v_mfma_f32_16x16x32_bf16 v[102:105], v[146:149], v[194:197], v[102:105]
	v_mfma_f32_16x16x32_bf16 v[98:101], v[164:167], v[194:197], v[98:101]
	v_mfma_f32_16x16x32_bf16 v[86:89], v[146:149], v[202:205], v[86:89]
	v_mfma_f32_16x16x32_bf16 v[82:85], v[164:167], v[202:205], v[82:85]
	v_mfma_f32_16x16x32_bf16 v[134:137], v[150:153], v[182:185], v[134:137]
	v_mfma_f32_16x16x32_bf16 v[130:133], v[168:171], v[182:185], v[130:133]
	v_mfma_f32_16x16x32_bf16 v[118:121], v[150:153], v[190:193], v[118:121]
	v_mfma_f32_16x16x32_bf16 v[114:117], v[168:171], v[190:193], v[114:117]
	v_mfma_f32_16x16x32_bf16 v[102:105], v[150:153], v[198:201], v[102:105]
	v_mfma_f32_16x16x32_bf16 v[98:101], v[168:171], v[198:201], v[98:101]
	v_mfma_f32_16x16x32_bf16 v[86:89], v[150:153], v[206:209], v[86:89]
	v_mfma_f32_16x16x32_bf16 v[82:85], v[168:171], v[206:209], v[82:85]
	s_setprio 0
	s_barrier
	s_mov_b32 m0, s49
	v_lshl_add_u64 v[210:211], v[210:211], 0, s[66:67]
	s_add_u32 s30, s30, 0x80080
	ds_read_b128 v[178:181], v174 offset:49152
	ds_read_b128 v[182:185], v174 offset:50176
	ds_read_b128 v[186:189], v174 offset:51200
	ds_read_b128 v[190:193], v174 offset:52224
	ds_read_b128 v[194:197], v174 offset:53248
	ds_read_b128 v[198:201], v174 offset:54272
	ds_read_b128 v[202:205], v174 offset:55296
	ds_read_b128 v[206:209], v174 offset:56320
	global_load_lds_dwordx4 v[210:211], off
	v_lshl_add_u64 v[210:211], v[212:213], 0, s[66:67]
	s_mov_b32 m0, s50
	s_addc_u32 s31, s31, 0
	global_load_lds_dwordx4 v[210:211], off
	s_mov_b32 m0, s58
	s_nop 0
	global_load_lds_dwordx4 v0, s[30:31]
	s_mov_b32 m0, s59
	s_nop 0
	global_load_lds_dwordx4 v158, s[30:31]
	v_lshl_add_u64 v[210:211], v[214:215], 0, s[66:67]
	s_mov_b32 m0, s51
	s_nop 0
	global_load_lds_dwordx4 v[210:211], off
	v_lshl_add_u64 v[210:211], v[216:217], 0, s[66:67]
	s_mov_b32 m0, s52
	s_nop 0
	global_load_lds_dwordx4 v[210:211], off
	s_waitcnt vmcnt(8)
	s_waitcnt lgkmcnt(0)
	s_barrier
	s_setprio 1
	s_waitcnt lgkmcnt(0)
	v_mfma_f32_16x16x32_bf16 v[78:81], v[50:53], v[178:181], v[78:81]
	v_mfma_f32_16x16x32_bf16 v[74:77], v[66:69], v[178:181], v[74:77]
	v_mfma_f32_16x16x32_bf16 v[62:65], v[50:53], v[186:189], v[62:65]
	v_mfma_f32_16x16x32_bf16 v[58:61], v[66:69], v[186:189], v[58:61]
	v_mfma_f32_16x16x32_bf16 v[38:41], v[50:53], v[194:197], v[38:41]
	v_mfma_f32_16x16x32_bf16 v[34:37], v[66:69], v[194:197], v[34:37]
	v_mfma_f32_16x16x32_bf16 v[14:17], v[50:53], v[202:205], v[14:17]
	v_mfma_f32_16x16x32_bf16 v[10:13], v[66:69], v[202:205], v[10:13]
	v_mfma_f32_16x16x32_bf16 v[78:81], v[54:57], v[182:185], v[78:81]
	v_mfma_f32_16x16x32_bf16 v[74:77], v[70:73], v[182:185], v[74:77]
	v_mfma_f32_16x16x32_bf16 v[62:65], v[54:57], v[190:193], v[62:65]
	v_mfma_f32_16x16x32_bf16 v[58:61], v[70:73], v[190:193], v[58:61]
	v_mfma_f32_16x16x32_bf16 v[38:41], v[54:57], v[198:201], v[38:41]
	v_mfma_f32_16x16x32_bf16 v[34:37], v[70:73], v[198:201], v[34:37]
	v_mfma_f32_16x16x32_bf16 v[14:17], v[54:57], v[206:209], v[14:17]
	v_mfma_f32_16x16x32_bf16 v[10:13], v[70:73], v[206:209], v[10:13]
	s_setprio 0
	s_setprio 1
	v_mfma_f32_16x16x32_bf16 v[26:29], v[146:149], v[178:181], v[26:29]
	v_mfma_f32_16x16x32_bf16 v[70:73], v[150:153], v[182:185], v[26:29]
	v_mfma_f32_16x16x32_bf16 v[26:29], v[164:167], v[178:181], v[30:33]
	v_mfma_f32_16x16x32_bf16 v[66:69], v[168:171], v[182:185], v[26:29]
	v_mfma_f32_16x16x32_bf16 v[26:29], v[146:149], v[186:189], v[42:45]
	v_mfma_f32_16x16x32_bf16 v[54:57], v[150:153], v[190:193], v[26:29]
	v_mfma_f32_16x16x32_bf16 v[26:29], v[164:167], v[186:189], v[46:49]
	v_mfma_f32_16x16x32_bf16 v[22:25], v[146:149], v[194:197], v[22:25]
	v_mfma_f32_16x16x32_bf16 v[18:21], v[164:167], v[194:197], v[18:21]
	v_mfma_f32_16x16x32_bf16 v[6:9], v[146:149], v[202:205], v[6:9]
	v_mfma_f32_16x16x32_bf16 v[2:5], v[164:167], v[202:205], v[2:5]
	v_mfma_f32_16x16x32_bf16 v[50:53], v[168:171], v[190:193], v[26:29]
	v_mfma_f32_16x16x32_bf16 v[22:25], v[150:153], v[198:201], v[22:25]
	v_mfma_f32_16x16x32_bf16 v[18:21], v[168:171], v[198:201], v[18:21]
	v_mfma_f32_16x16x32_bf16 v[6:9], v[150:153], v[206:209], v[6:9]
	v_mfma_f32_16x16x32_bf16 v[2:5], v[168:171], v[206:209], v[2:5]
	s_setprio 0
	s_barrier
	s_add_i32 s56, s56, 2
	s_add_u32 s28, s28, 0x100
	s_addc_u32 s29, s29, 0
	s_add_u32 s23, s23, 0x100
	s_addc_u32 s54, s54, 0
	s_cmp_gt_u32 s56, 29
	s_cbranch_scc0 .LBB0_200
	s_and_b64 vcc, exec, s[14:15]
	s_cbranch_vccz .LBB0_203
	s_barrier

; #define PG8_STAGE(bufoff, gbase, voff) do { _Pragma("unroll") for (int _i = 0; _i < 2; ++_i) \
;         __builtin_amdgcn_global_load_lds((const unsigned*)((const char*)(gbase) + (voff)[_i]), (LAS unsigned*)(lds + (bufoff) + ldsw + _i * 8192), 16, 0, 0); } while (0)
; #define PG8_LDA(dst, b, h) do { _Pragma("unroll") for (int m = 0; m < NM; ++m) _Pragma("unroll") for (int k = 0; k < 2; ++k) dst[m][k] = *(const LAS bf16x8*)(lds + PG8_SA(b, h) + aoff + m * 2048 + k * 1024); } while (0)
; #define PG8_LDB(dst, b, h) do { _Pragma("unroll") for (int n = 0; n < 2; ++n) _Pragma("unroll") for (int k = 0; k < 2; ++k) dst[n][k] = *(const LAS bf16x8*)(lds + PG8_SB(b, h) + boff + n * 2048 + k * 1024); } while (0)
; #define PG8_MMA(ai, bj, At, Bt) do { __builtin_amdgcn_s_setprio(1); _Pragma("unroll") for (int m = 0; m < NM; ++m) _Pragma("unroll") for (int n = 0; n < 2; ++n) _Pragma("unroll") for (int k = 0; k < 2; ++k) \
;         acc[ai][bj][m][n] = __builtin_amdgcn_mfma_f32_16x16x32_bf16(Bt[n][k], At[m][k], acc[ai][bj][m][n], 0, 0, 0); __builtin_amdgcn_s_setprio(0); } while (0)
; #define PG8_WAIT_V(n) asm volatile("s_waitcnt vmcnt(" #n ")" ::: "memory")
; #define PG8_WAIT_L(n) asm volatile("s_waitcnt lgkmcnt(" #n ")" ::: "memory")
; #define PG8_BAR __builtin_amdgcn_s_barrier()
; #define PG8_SCHED __builtin_amdgcn_sched_barrier(0)
;     ...
;         for (int t = 0; t < nt; t += 2) {
;             const bool last = (t == nt - 2);
;             const char* a1 = cA + (size_t)(t + 1) * kstep;
;             const char* a2 = last ? nA : cA + (size_t)(t + 2) * kstep; const char* b2 = last ? nB : cB + (size_t)(t + 2) * kstep;
;             const char* a3 = a2 + kstep; const char* b3 = b2 + kstep;
;             if constexpr (SP2) {
;             PG8_LDB(B0, 0, 0); PG8_LDB(B1, 0, 1); PG8_SCHED; PG8_LDA(At, 0, 0); PG8_STAGE(PG8_SA(1, 1), a1 + hstepA, voffA);
;             PG8_WAIT_V(8); PG8_WAIT_L(0); PG8_BAR; PG8_MMA(0, 0, At, B0); PG8_MMA(0, 1, At, B1); PG8_BAR; PG8_SCHED;
;             PG8_LDA(At, 0, 1); PG8_STAGE(PG8_SB(0, 0), b2, voffB); PG8_STAGE(PG8_SB(0, 1), b2 + hstepB, voffB); PG8_STAGE(PG8_SA(0, 0), a2, voffA);
;             PG8_WAIT_V(8); PG8_WAIT_L(0); PG8_BAR; PG8_MMA(1, 0, At, B0); PG8_MMA(1, 1, At, B1); PG8_BAR; PG8_SCHED;
.LBB0_703:
	v_add_u32_e32 v0, s50, v146
	ds_read_b128 v[138:141], v0
	ds_read_b128 v[142:145], v0 offset:1024
	ds_read_b128 v[148:151], v0 offset:2048
	ds_read_b128 v[152:155], v0 offset:3072
	v_add_u32_e32 v0, s54, v146
	ds_read_b128 v[156:159], v0
	ds_read_b128 v[160:163], v0 offset:1024
	ds_read_b128 v[164:167], v0 offset:2048
	ds_read_b128 v[168:171], v0 offset:3072
	s_add_u32 s12, s10, 0xfff80080
	s_addc_u32 s13, s11, -1
	s_cmp_eq_u32 s39, 28
	s_cselect_b32 s37, s2, s13
	s_cselect_b32 s36, s3, s12
	s_cselect_b32 s13, s9, s38
	s_cselect_b32 s12, s27, s29
	s_add_i32 m0, s58, 0xc000
	ds_read_b128 v[172:175], v147
	ds_read_b128 v[176:179], v147 offset:1024
	ds_read_b128 v[180:183], v147 offset:2048
	ds_read_b128 v[184:187], v147 offset:3072
	ds_read_b128 v[188:191], v147 offset:4096
	ds_read_b128 v[192:195], v147 offset:5120
	ds_read_b128 v[196:199], v147 offset:6144
	ds_read_b128 v[200:203], v147 offset:7168
	global_load_lds_dwordx4 v134, s[10:11]
	s_add_i32 m0, s58, 0xe000
	s_nop 0
	global_load_lds_dwordx4 v136, s[10:11]
	s_waitcnt vmcnt(8)
	s_waitcnt lgkmcnt(0)
	s_barrier
	s_setprio 1
	s_waitcnt lgkmcnt(0)
	v_mfma_f32_16x16x32_bf16 v[126:129], v[138:141], v[172:175], v[126:129]
	v_mfma_f32_16x16x32_bf16 v[122:125], v[148:151], v[172:175], v[122:125]
	v_mfma_f32_16x16x32_bf16 v[110:113], v[138:141], v[180:183], v[110:113]
	v_mfma_f32_16x16x32_bf16 v[106:109], v[148:151], v[180:183], v[106:109]
	v_mfma_f32_16x16x32_bf16 v[94:97], v[138:141], v[188:191], v[94:97]
	v_mfma_f32_16x16x32_bf16 v[90:93], v[148:151], v[188:191], v[90:93]
	v_mfma_f32_16x16x32_bf16 v[78:81], v[138:141], v[196:199], v[78:81]
	v_mfma_f32_16x16x32_bf16 v[74:77], v[148:151], v[196:199], v[74:77]
	v_mfma_f32_16x16x32_bf16 v[126:129], v[142:145], v[176:179], v[126:129]
	v_mfma_f32_16x16x32_bf16 v[122:125], v[152:155], v[176:179], v[122:125]
	v_mfma_f32_16x16x32_bf16 v[110:113], v[142:145], v[184:187], v[110:113]
	v_mfma_f32_16x16x32_bf16 v[106:109], v[152:155], v[184:187], v[106:109]
	v_mfma_f32_16x16x32_bf16 v[94:97], v[142:145], v[192:195], v[94:97]
	v_mfma_f32_16x16x32_bf16 v[90:93], v[152:155], v[192:195], v[90:93]
	v_mfma_f32_16x16x32_bf16 v[78:81], v[142:145], v[200:203], v[78:81]
	v_mfma_f32_16x16x32_bf16 v[74:77], v[152:155], v[200:203], v[74:77]
	s_setprio 0
	s_setprio 1
	v_mfma_f32_16x16x32_bf16 v[118:121], v[156:159], v[172:175], v[118:121]
	v_mfma_f32_16x16x32_bf16 v[114:117], v[164:167], v[172:175], v[114:117]
	v_mfma_f32_16x16x32_bf16 v[102:105], v[156:159], v[180:183], v[102:105]
	v_mfma_f32_16x16x32_bf16 v[98:101], v[164:167], v[180:183], v[98:101]
	v_mfma_f32_16x16x32_bf16 v[86:89], v[156:159], v[188:191], v[86:89]
	v_mfma_f32_16x16x32_bf16 v[82:85], v[164:167], v[188:191], v[82:85]
	v_mfma_f32_16x16x32_bf16 v[70:73], v[156:159], v[196:199], v[70:73]
	v_mfma_f32_16x16x32_bf16 v[66:69], v[164:167], v[196:199], v[66:69]
	v_mfma_f32_16x16x32_bf16 v[118:121], v[160:163], v[176:179], v[118:121]
	v_mfma_f32_16x16x32_bf16 v[114:117], v[168:171], v[176:179], v[114:117]
	v_mfma_f32_16x16x32_bf16 v[102:105], v[160:163], v[184:187], v[102:105]
	v_mfma_f32_16x16x32_bf16 v[98:101], v[168:171], v[184:187], v[98:101]
	v_mfma_f32_16x16x32_bf16 v[86:89], v[160:163], v[192:195], v[86:89]
	v_mfma_f32_16x16x32_bf16 v[82:85], v[168:171], v[192:195], v[82:85]
	v_mfma_f32_16x16x32_bf16 v[70:73], v[160:163], v[200:203], v[70:73]
	v_mfma_f32_16x16x32_bf16 v[66:69], v[168:171], v[200:203], v[66:69]
	s_setprio 0
	s_barrier
	s_mov_b32 m0, s51
	v_lshl_add_u64 v[204:205], s[12:13], 0, v[130:131]
	s_add_u32 s40, s12, 0x80000
	ds_read_b128 v[172:175], v147 offset:16384
	ds_read_b128 v[176:179], v147 offset:17408
	ds_read_b128 v[180:183], v147 offset:18432
	ds_read_b128 v[184:187], v147 offset:19456
	ds_read_b128 v[188:191], v147 offset:20480
	ds_read_b128 v[192:195], v147 offset:21504
	ds_read_b128 v[196:199], v147 offset:22528
	ds_read_b128 v[200:203], v147 offset:23552
	global_load_lds_dwordx4 v130, s[12:13]
	v_lshl_add_u64 v[206:207], s[12:13], 0, v[132:133]
	s_mov_b32 m0, s52
	s_addc_u32 s41, s13, 0
	global_load_lds_dwordx4 v132, s[12:13]
	s_mov_b32 m0, s56
	v_lshl_add_u64 v[210:211], s[36:37], 0, v[132:133]
	global_load_lds_dwordx4 v130, s[40:41]
	s_mov_b32 m0, s57
	s_nop 0
	global_load_lds_dwordx4 v132, s[40:41]
	v_lshl_add_u64 v[208:209], s[36:37], 0, v[130:131]
	s_mov_b32 m0, s58
	s_nop 0
	global_load_lds_dwordx4 v130, s[36:37]
	s_mov_b32 m0, s59
	s_nop 0
	global_load_lds_dwordx4 v132, s[36:37]
	s_waitcnt vmcnt(8)
	s_waitcnt lgkmcnt(0)
	s_barrier
	s_setprio 1
	s_waitcnt lgkmcnt(0)
	v_mfma_f32_16x16x32_bf16 v[62:65], v[138:141], v[172:175], v[62:65]
	v_mfma_f32_16x16x32_bf16 v[58:61], v[148:151], v[172:175], v[58:61]
	v_mfma_f32_16x16x32_bf16 v[46:49], v[138:141], v[180:183], v[46:49]
	v_mfma_f32_16x16x32_bf16 v[42:45], v[148:151], v[180:183], v[42:45]
	v_mfma_f32_16x16x32_bf16 v[30:33], v[138:141], v[188:191], v[30:33]
	v_mfma_f32_16x16x32_bf16 v[26:29], v[148:151], v[188:191], v[26:29]
	v_mfma_f32_16x16x32_bf16 v[14:17], v[138:141], v[196:199], v[14:17]
	v_mfma_f32_16x16x32_bf16 v[10:13], v[148:151], v[196:199], v[10:13]
	v_mfma_f32_16x16x32_bf16 v[62:65], v[142:145], v[176:179], v[62:65]
	v_mfma_f32_16x16x32_bf16 v[58:61], v[152:155], v[176:179], v[58:61]
	v_mfma_f32_16x16x32_bf16 v[46:49], v[142:145], v[184:187], v[46:49]
	v_mfma_f32_16x16x32_bf16 v[42:45], v[152:155], v[184:187], v[42:45]
	v_mfma_f32_16x16x32_bf16 v[30:33], v[142:145], v[192:195], v[30:33]
	v_mfma_f32_16x16x32_bf16 v[26:29], v[152:155], v[192:195], v[26:29]
	v_mfma_f32_16x16x32_bf16 v[14:17], v[142:145], v[200:203], v[14:17]
	v_mfma_f32_16x16x32_bf16 v[10:13], v[152:155], v[200:203], v[10:13]
	s_setprio 0
	s_setprio 1
	v_mfma_f32_16x16x32_bf16 v[54:57], v[156:159], v[172:175], v[54:57]
	v_mfma_f32_16x16x32_bf16 v[50:53], v[164:167], v[172:175], v[50:53]
	v_mfma_f32_16x16x32_bf16 v[38:41], v[156:159], v[180:183], v[38:41]
	v_mfma_f32_16x16x32_bf16 v[34:37], v[164:167], v[180:183], v[34:37]
	v_mfma_f32_16x16x32_bf16 v[22:25], v[156:159], v[188:191], v[22:25]
	v_mfma_f32_16x16x32_bf16 v[18:21], v[164:167], v[188:191], v[18:21]
	v_mfma_f32_16x16x32_bf16 v[6:9], v[156:159], v[196:199], v[6:9]
	v_mfma_f32_16x16x32_bf16 v[2:5], v[164:167], v[196:199], v[2:5]
	v_mfma_f32_16x16x32_bf16 v[54:57], v[160:163], v[176:179], v[54:57]
	v_mfma_f32_16x16x32_bf16 v[50:53], v[168:171], v[176:179], v[50:53]
	v_mfma_f32_16x16x32_bf16 v[38:41], v[160:163], v[184:187], v[38:41]
	v_mfma_f32_16x16x32_bf16 v[34:37], v[168:171], v[184:187], v[34:37]
	v_mfma_f32_16x16x32_bf16 v[22:25], v[160:163], v[192:195], v[22:25]
	v_mfma_f32_16x16x32_bf16 v[18:21], v[168:171], v[192:195], v[18:21]
	v_mfma_f32_16x16x32_bf16 v[6:9], v[160:163], v[200:203], v[6:9]
	v_mfma_f32_16x16x32_bf16 v[2:5], v[168:171], v[200:203], v[2:5]
	s_setprio 0
	s_barrier
; #define PG8_STAGE(bufoff, gbase, voff) do { _Pragma("unroll") for (int _i = 0; _i < 2; ++_i) \
;         __builtin_amdgcn_global_load_lds((const unsigned*)((const char*)(gbase) + (voff)[_i]), (LAS unsigned*)(lds + (bufoff) + ldsw + _i * 8192), 16, 0, 0); } while (0)
; #define PG8_LDA(dst, b, h) do { _Pragma("unroll") for (int m = 0; m < NM; ++m) _Pragma("unroll") for (int k = 0; k < 2; ++k) dst[m][k] = *(const LAS bf16x8*)(lds + PG8_SA(b, h) + aoff + m * 2048 + k * 1024); } while (0)
; #define PG8_LDB(dst, b, h) do { _Pragma("unroll") for (int n = 0; n < 2; ++n) _Pragma("unroll") for (int k = 0; k < 2; ++k) dst[n][k] = *(const LAS bf16x8*)(lds + PG8_SB(b, h) + boff + n * 2048 + k * 1024); } while (0)
; #define PG8_MMA(ai, bj, At, Bt) do { __builtin_amdgcn_s_setprio(1); _Pragma("unroll") for (int m = 0; m < NM; ++m) _Pragma("unroll") for (int n = 0; n < 2; ++n) _Pragma("unroll") for (int k = 0; k < 2; ++k) \
;         acc[ai][bj][m][n] = __builtin_amdgcn_mfma_f32_16x16x32_bf16(Bt[n][k], At[m][k], acc[ai][bj][m][n], 0, 0, 0); __builtin_amdgcn_s_setprio(0); } while (0)
; #define PG8_WAIT_V(n) asm volatile("s_waitcnt vmcnt(" #n ")" ::: "memory")
; #define PG8_WAIT_L(n) asm volatile("s_waitcnt lgkmcnt(" #n ")" ::: "memory")
; #define PG8_BAR __builtin_amdgcn_s_barrier()
; #define PG8_SCHED __builtin_amdgcn_sched_barrier(0)
;     ...
;             PG8_LDB(B0, 1, 0); PG8_LDB(B1, 1, 1); PG8_SCHED; PG8_LDA(At, 1, 0); PG8_STAGE(PG8_SA(0, 1), a2 + hstepA, voffA);
;             PG8_WAIT_V(8); PG8_WAIT_L(0); PG8_BAR; PG8_MMA(0, 0, At, B0); PG8_MMA(0, 1, At, B1); PG8_BAR; PG8_SCHED;
;             PG8_LDA(At, 1, 1); PG8_STAGE(PG8_SB(1, 0), b3, voffB); PG8_STAGE(PG8_SB(1, 1), b3 + hstepB, voffB); PG8_STAGE(PG8_SA(1, 0), a3, voffA);
;             PG8_WAIT_V(8); PG8_WAIT_L(0); PG8_BAR; PG8_MMA(1, 0, At, B0); PG8_MMA(1, 1, At, B1); PG8_BAR; PG8_SCHED;
	v_add_u32_e32 v0, s64, v146
	ds_read_b128 v[138:141], v0
	ds_read_b128 v[142:145], v0 offset:1024
	ds_read_b128 v[148:151], v0 offset:2048
	ds_read_b128 v[152:155], v0 offset:3072
	v_add_u32_e32 v0, s71, v146
	ds_read_b128 v[156:159], v0
	ds_read_b128 v[160:163], v0 offset:1024
	ds_read_b128 v[164:167], v0 offset:2048
	ds_read_b128 v[168:171], v0 offset:3072
	s_add_u32 s36, s36, 0x80000
	s_addc_u32 s37, s37, 0
	s_mov_b32 m0, s62
	ds_read_b128 v[172:175], v147 offset:32768
	ds_read_b128 v[176:179], v147 offset:33792
	ds_read_b128 v[180:183], v147 offset:34816
	ds_read_b128 v[184:187], v147 offset:35840
	ds_read_b128 v[188:191], v147 offset:36864
	ds_read_b128 v[192:195], v147 offset:37888
	ds_read_b128 v[196:199], v147 offset:38912
	ds_read_b128 v[200:203], v147 offset:39936
	global_load_lds_dwordx4 v130, s[36:37]
	s_mov_b32 m0, s63
	s_nop 0
	global_load_lds_dwordx4 v132, s[36:37]
	s_waitcnt vmcnt(8)
	s_waitcnt lgkmcnt(0)
	s_barrier
	s_setprio 1
	s_waitcnt lgkmcnt(0)
	v_mfma_f32_16x16x32_bf16 v[126:129], v[138:141], v[172:175], v[126:129]
	v_mfma_f32_16x16x32_bf16 v[122:125], v[148:151], v[172:175], v[122:125]
	v_mfma_f32_16x16x32_bf16 v[110:113], v[138:141], v[180:183], v[110:113]
	v_mfma_f32_16x16x32_bf16 v[106:109], v[148:151], v[180:183], v[106:109]
	v_mfma_f32_16x16x32_bf16 v[94:97], v[138:141], v[188:191], v[94:97]
	v_mfma_f32_16x16x32_bf16 v[90:93], v[148:151], v[188:191], v[90:93]
	v_mfma_f32_16x16x32_bf16 v[78:81], v[138:141], v[196:199], v[78:81]
	v_mfma_f32_16x16x32_bf16 v[74:77], v[148:151], v[196:199], v[74:77]
	v_mfma_f32_16x16x32_bf16 v[126:129], v[142:145], v[176:179], v[126:129]
	v_mfma_f32_16x16x32_bf16 v[122:125], v[152:155], v[176:179], v[122:125]
	v_mfma_f32_16x16x32_bf16 v[110:113], v[142:145], v[184:187], v[110:113]
	v_mfma_f32_16x16x32_bf16 v[106:109], v[152:155], v[184:187], v[106:109]
	v_mfma_f32_16x16x32_bf16 v[94:97], v[142:145], v[192:195], v[94:97]
	v_mfma_f32_16x16x32_bf16 v[90:93], v[152:155], v[192:195], v[90:93]
	v_mfma_f32_16x16x32_bf16 v[78:81], v[142:145], v[200:203], v[78:81]
	v_mfma_f32_16x16x32_bf16 v[74:77], v[152:155], v[200:203], v[74:77]
	s_setprio 0
	s_setprio 1
	v_mfma_f32_16x16x32_bf16 v[118:121], v[156:159], v[172:175], v[118:121]
	v_mfma_f32_16x16x32_bf16 v[114:117], v[164:167], v[172:175], v[114:117]
	v_mfma_f32_16x16x32_bf16 v[102:105], v[156:159], v[180:183], v[102:105]
	v_mfma_f32_16x16x32_bf16 v[98:101], v[164:167], v[180:183], v[98:101]
	v_mfma_f32_16x16x32_bf16 v[86:89], v[156:159], v[188:191], v[86:89]
	v_mfma_f32_16x16x32_bf16 v[82:85], v[164:167], v[188:191], v[82:85]
	v_mfma_f32_16x16x32_bf16 v[70:73], v[156:159], v[196:199], v[70:73]
	v_mfma_f32_16x16x32_bf16 v[66:69], v[164:167], v[196:199], v[66:69]
	v_mfma_f32_16x16x32_bf16 v[118:121], v[160:163], v[176:179], v[118:121]
	v_mfma_f32_16x16x32_bf16 v[114:117], v[168:171], v[176:179], v[114:117]
	v_mfma_f32_16x16x32_bf16 v[102:105], v[160:163], v[184:187], v[102:105]
	v_mfma_f32_16x16x32_bf16 v[98:101], v[168:171], v[184:187], v[98:101]
	v_mfma_f32_16x16x32_bf16 v[86:89], v[160:163], v[192:195], v[86:89]
	v_mfma_f32_16x16x32_bf16 v[82:85], v[168:171], v[192:195], v[82:85]
	v_mfma_f32_16x16x32_bf16 v[70:73], v[160:163], v[200:203], v[70:73]
	v_mfma_f32_16x16x32_bf16 v[66:69], v[168:171], v[200:203], v[66:69]
	s_setprio 0
	s_barrier
	s_mov_b32 m0, s65
	v_lshl_add_u64 v[204:205], v[204:205], 0, s[66:67]
	s_add_u32 s12, s12, 0x80080
	ds_read_b128 v[172:175], v147 offset:49152
	ds_read_b128 v[176:179], v147 offset:50176
	ds_read_b128 v[180:183], v147 offset:51200
	ds_read_b128 v[184:187], v147 offset:52224
	ds_read_b128 v[188:191], v147 offset:53248
	ds_read_b128 v[192:195], v147 offset:54272
	ds_read_b128 v[196:199], v147 offset:55296
	ds_read_b128 v[200:203], v147 offset:56320
	global_load_lds_dwordx4 v[204:205], off
	v_lshl_add_u64 v[204:205], v[206:207], 0, s[66:67]
	s_mov_b32 m0, s68
	s_addc_u32 s13, s13, 0
	global_load_lds_dwordx4 v[204:205], off
	s_mov_b32 m0, s72
	s_nop 0
	global_load_lds_dwordx4 v130, s[12:13]
	s_mov_b32 m0, s73
	s_nop 0
	global_load_lds_dwordx4 v132, s[12:13]
	v_lshl_add_u64 v[204:205], v[208:209], 0, s[66:67]
	s_mov_b32 m0, s69
	s_nop 0
	global_load_lds_dwordx4 v[204:205], off
	v_lshl_add_u64 v[204:205], v[210:211], 0, s[66:67]
	s_mov_b32 m0, s70
	s_nop 0
	global_load_lds_dwordx4 v[204:205], off
	s_waitcnt vmcnt(8)
	s_waitcnt lgkmcnt(0)
	s_barrier
	s_setprio 1
	s_waitcnt lgkmcnt(0)
	v_mfma_f32_16x16x32_bf16 v[62:65], v[138:141], v[172:175], v[62:65]
	v_mfma_f32_16x16x32_bf16 v[58:61], v[148:151], v[172:175], v[58:61]
	v_mfma_f32_16x16x32_bf16 v[46:49], v[138:141], v[180:183], v[46:49]
	v_mfma_f32_16x16x32_bf16 v[42:45], v[148:151], v[180:183], v[42:45]
	v_mfma_f32_16x16x32_bf16 v[30:33], v[138:141], v[188:191], v[30:33]
	v_mfma_f32_16x16x32_bf16 v[26:29], v[148:151], v[188:191], v[26:29]
	v_mfma_f32_16x16x32_bf16 v[14:17], v[138:141], v[196:199], v[14:17]
	v_mfma_f32_16x16x32_bf16 v[10:13], v[148:151], v[196:199], v[10:13]
	v_mfma_f32_16x16x32_bf16 v[62:65], v[142:145], v[176:179], v[62:65]
	v_mfma_f32_16x16x32_bf16 v[58:61], v[152:155], v[176:179], v[58:61]
	v_mfma_f32_16x16x32_bf16 v[46:49], v[142:145], v[184:187], v[46:49]
	v_mfma_f32_16x16x32_bf16 v[42:45], v[152:155], v[184:187], v[42:45]
	v_mfma_f32_16x16x32_bf16 v[30:33], v[142:145], v[192:195], v[30:33]
	v_mfma_f32_16x16x32_bf16 v[26:29], v[152:155], v[192:195], v[26:29]
	v_mfma_f32_16x16x32_bf16 v[14:17], v[142:145], v[200:203], v[14:17]
	v_mfma_f32_16x16x32_bf16 v[10:13], v[152:155], v[200:203], v[10:13]
	s_setprio 0
	s_setprio 1
	v_mfma_f32_16x16x32_bf16 v[54:57], v[156:159], v[172:175], v[54:57]
	v_mfma_f32_16x16x32_bf16 v[50:53], v[164:167], v[172:175], v[50:53]
	v_mfma_f32_16x16x32_bf16 v[38:41], v[156:159], v[180:183], v[38:41]
	v_mfma_f32_16x16x32_bf16 v[34:37], v[164:167], v[180:183], v[34:37]
	v_mfma_f32_16x16x32_bf16 v[22:25], v[156:159], v[188:191], v[22:25]
	v_mfma_f32_16x16x32_bf16 v[18:21], v[164:167], v[188:191], v[18:21]
	v_mfma_f32_16x16x32_bf16 v[6:9], v[156:159], v[196:199], v[6:9]
	v_mfma_f32_16x16x32_bf16 v[2:5], v[164:167], v[196:199], v[2:5]
	v_mfma_f32_16x16x32_bf16 v[54:57], v[160:163], v[176:179], v[54:57]
	v_mfma_f32_16x16x32_bf16 v[50:53], v[168:171], v[176:179], v[50:53]
	v_mfma_f32_16x16x32_bf16 v[38:41], v[160:163], v[184:187], v[38:41]
	v_mfma_f32_16x16x32_bf16 v[34:37], v[168:171], v[184:187], v[34:37]
	v_mfma_f32_16x16x32_bf16 v[22:25], v[160:163], v[192:195], v[22:25]
	v_mfma_f32_16x16x32_bf16 v[18:21], v[168:171], v[192:195], v[18:21]
	v_mfma_f32_16x16x32_bf16 v[6:9], v[160:163], v[200:203], v[6:9]
	v_mfma_f32_16x16x32_bf16 v[2:5], v[168:171], v[200:203], v[2:5]
	s_setprio 0
	s_barrier
	s_add_i32 s39, s39, 2
	s_add_u32 s10, s10, 0x100
	s_addc_u32 s11, s11, 0
	s_add_u32 s29, s29, 0x100
	s_addc_u32 s38, s38, 0
	s_cmp_gt_u32 s39, 29
	s_cbranch_scc0 .LBB0_703
	s_and_b64 vcc, exec, s[18:19]
	s_cbranch_vccz .LBB0_706
	s_barrier

; #define PG8_STAGE(bufoff, gbase, voff) do { _Pragma("unroll") for (int _i = 0; _i < 2; ++_i) \
;         __builtin_amdgcn_global_load_lds((const unsigned*)((const char*)(gbase) + (voff)[_i]), (LAS unsigned*)(lds + (bufoff) + ldsw + _i * 8192), 16, 0, 0); } while (0)
; #define PG8_LDA(dst, b, h) do { _Pragma("unroll") for (int m = 0; m < NM; ++m) _Pragma("unroll") for (int k = 0; k < 2; ++k) dst[m][k] = *(const LAS bf16x8*)(lds + PG8_SA(b, h) + aoff + m * 2048 + k * 1024); } while (0)
; #define PG8_LDB(dst, b, h) do { _Pragma("unroll") for (int n = 0; n < 2; ++n) _Pragma("unroll") for (int k = 0; k < 2; ++k) dst[n][k] = *(const LAS bf16x8*)(lds + PG8_SB(b, h) + boff + n * 2048 + k * 1024); } while (0)
; #define PG8_MMA(ai, bj, At, Bt) do { __builtin_amdgcn_s_setprio(1); _Pragma("unroll") for (int m = 0; m < NM; ++m) _Pragma("unroll") for (int n = 0; n < 2; ++n) _Pragma("unroll") for (int k = 0; k < 2; ++k) \
;         acc[ai][bj][m][n] = __builtin_amdgcn_mfma_f32_16x16x32_bf16(Bt[n][k], At[m][k], acc[ai][bj][m][n], 0, 0, 0); __builtin_amdgcn_s_setprio(0); } while (0)
; #define PG8_WAIT_V(n) asm volatile("s_waitcnt vmcnt(" #n ")" ::: "memory")
; #define PG8_WAIT_L(n) asm volatile("s_waitcnt lgkmcnt(" #n ")" ::: "memory")
; #define PG8_BAR __builtin_amdgcn_s_barrier()
; #define PG8_SCHED __builtin_amdgcn_sched_barrier(0)
;     ...
;         for (int t = 0; t < nt; t += 2) {
;             const bool last = (t == nt - 2);
;             const char* a1 = cA + (size_t)(t + 1) * kstep;
;             const char* a2 = last ? nA : cA + (size_t)(t + 2) * kstep; const char* b2 = last ? nB : cB + (size_t)(t + 2) * kstep;
;             const char* a3 = a2 + kstep; const char* b3 = b2 + kstep;
;             if constexpr (SP2) {
;             PG8_LDB(B0, 0, 0); PG8_LDB(B1, 0, 1); PG8_SCHED; PG8_LDA(At, 0, 0); PG8_STAGE(PG8_SA(1, 1), a1 + hstepA, voffA);
;             PG8_WAIT_V(8); PG8_WAIT_L(0); PG8_BAR; PG8_MMA(0, 0, At, B0); PG8_MMA(0, 1, At, B1); PG8_BAR; PG8_SCHED;
;             PG8_LDA(At, 0, 1); PG8_STAGE(PG8_SB(0, 0), b2, voffB); PG8_STAGE(PG8_SB(0, 1), b2 + hstepB, voffB); PG8_STAGE(PG8_SA(0, 0), a2, voffA);
;             PG8_WAIT_V(8); PG8_WAIT_L(0); PG8_BAR; PG8_MMA(1, 0, At, B0); PG8_MMA(1, 1, At, B1); PG8_BAR; PG8_SCHED;
.LBB0_1192:
	v_add_u32_e32 v0, s49, v216
	ds_read_b128 v[10:13], v0
	ds_read_b128 v[14:17], v0 offset:1024
	ds_read_b128 v[18:21], v0 offset:2048
	ds_read_b128 v[22:25], v0 offset:3072
	v_add_u32_e32 v0, s58, v216
	ds_read_b128 v[26:29], v0
	ds_read_b128 v[30:33], v0 offset:1024
	ds_read_b128 v[42:45], v0 offset:2048
	ds_read_b128 v[46:49], v0 offset:3072
	s_add_u32 s12, s10, 0xfffe0080
	s_addc_u32 s13, s11, -1
	s_cmp_eq_u32 s54, 4
	s_cselect_b32 s35, s2, s13
	s_cselect_b32 s34, s3, s12
	s_cselect_b32 s13, s7, s52
	s_cselect_b32 s12, s27, s9
	s_add_i32 m0, s62, 0xc000
	ds_read_b128 v[50:53], v217
	ds_read_b128 v[54:57], v217 offset:1024
	ds_read_b128 v[58:61], v217 offset:2048
	ds_read_b128 v[62:65], v217 offset:3072
	ds_read_b128 v[178:181], v217 offset:4096
	ds_read_b128 v[182:185], v217 offset:5120
	ds_read_b128 v[198:201], v217 offset:6144
	ds_read_b128 v[208:211], v217 offset:7168
	global_load_lds_dwordx4 v194, s[10:11]
	s_add_i32 m0, s62, 0xe000
	s_nop 0
	global_load_lds_dwordx4 v196, s[10:11]
	s_waitcnt vmcnt(8)
	s_waitcnt lgkmcnt(0)
	s_barrier
	s_setprio 1
	s_waitcnt lgkmcnt(0)
	v_mfma_f32_16x16x32_bf16 v[38:41], v[10:13], v[50:53], v[38:41]
	v_mfma_f32_16x16x32_bf16 v[34:37], v[18:21], v[50:53], v[34:37]
	v_mfma_f32_16x16x32_bf16 v[174:177], v[10:13], v[58:61], v[174:177]
	v_mfma_f32_16x16x32_bf16 v[170:173], v[18:21], v[58:61], v[170:173]
	v_mfma_f32_16x16x32_bf16 v[158:161], v[10:13], v[178:181], v[158:161]
	v_mfma_f32_16x16x32_bf16 v[154:157], v[18:21], v[178:181], v[154:157]
	v_mfma_f32_16x16x32_bf16 v[142:145], v[10:13], v[198:201], v[142:145]
	v_mfma_f32_16x16x32_bf16 v[138:141], v[18:21], v[198:201], v[138:141]
	v_mfma_f32_16x16x32_bf16 v[38:41], v[14:17], v[54:57], v[38:41]
	v_mfma_f32_16x16x32_bf16 v[34:37], v[22:25], v[54:57], v[34:37]
	v_mfma_f32_16x16x32_bf16 v[174:177], v[14:17], v[62:65], v[174:177]
	v_mfma_f32_16x16x32_bf16 v[170:173], v[22:25], v[62:65], v[170:173]
	v_mfma_f32_16x16x32_bf16 v[158:161], v[14:17], v[182:185], v[158:161]
	v_mfma_f32_16x16x32_bf16 v[154:157], v[22:25], v[182:185], v[154:157]
	v_mfma_f32_16x16x32_bf16 v[142:145], v[14:17], v[208:211], v[142:145]
	v_mfma_f32_16x16x32_bf16 v[138:141], v[22:25], v[208:211], v[138:141]
	s_setprio 0
	s_setprio 1
	v_mfma_f32_16x16x32_bf16 v[6:9], v[26:29], v[50:53], v[6:9]
	v_mfma_f32_16x16x32_bf16 v[2:5], v[42:45], v[50:53], v[2:5]
	v_mfma_f32_16x16x32_bf16 v[6:9], v[30:33], v[54:57], v[6:9]
	v_mfma_f32_16x16x32_bf16 v[2:5], v[46:49], v[54:57], v[2:5]
	v_mfma_f32_16x16x32_bf16 v[50:53], v[26:29], v[58:61], v[166:169]
	v_mfma_f32_16x16x32_bf16 v[54:57], v[42:45], v[58:61], v[162:165]
	v_mfma_f32_16x16x32_bf16 v[134:137], v[26:29], v[198:201], v[134:137]
	v_mfma_f32_16x16x32_bf16 v[130:133], v[42:45], v[198:201], v[130:133]
	v_mfma_f32_16x16x32_bf16 v[50:53], v[30:33], v[62:65], v[50:53]
	v_mfma_f32_16x16x32_bf16 v[54:57], v[46:49], v[62:65], v[54:57]
	v_mfma_f32_16x16x32_bf16 v[58:61], v[26:29], v[178:181], v[150:153]
	v_mfma_f32_16x16x32_bf16 v[62:65], v[42:45], v[178:181], v[146:149]
	v_mfma_f32_16x16x32_bf16 v[134:137], v[30:33], v[208:211], v[134:137]
	v_mfma_f32_16x16x32_bf16 v[130:133], v[46:49], v[208:211], v[130:133]
	v_mfma_f32_16x16x32_bf16 v[58:61], v[30:33], v[182:185], v[58:61]
	v_mfma_f32_16x16x32_bf16 v[62:65], v[46:49], v[182:185], v[62:65]
	s_setprio 0
	s_barrier
	s_mov_b32 m0, s50
	v_lshl_add_u64 v[202:203], s[12:13], 0, v[188:189]
	s_add_u32 s56, s12, 0x20000
	ds_read_b128 v[146:149], v217 offset:16384
	ds_read_b128 v[150:153], v217 offset:17408
	ds_read_b128 v[162:165], v217 offset:18432
	ds_read_b128 v[166:169], v217 offset:19456
	ds_read_b128 v[178:181], v217 offset:20480
	ds_read_b128 v[182:185], v217 offset:21504
	ds_read_b128 v[198:201], v217 offset:22528
	ds_read_b128 v[208:211], v217 offset:23552
	global_load_lds_dwordx4 v188, s[12:13]
	v_lshl_add_u64 v[204:205], s[12:13], 0, v[192:193]
	s_mov_b32 m0, s51
	s_addc_u32 s57, s13, 0
	global_load_lds_dwordx4 v192, s[12:13]
	s_mov_b32 m0, s59
	v_lshl_add_u64 v[222:223], s[34:35], 0, v[190:191]
	global_load_lds_dwordx4 v188, s[56:57]
	s_mov_b32 m0, s60
	s_nop 0
	global_load_lds_dwordx4 v192, s[56:57]
	v_lshl_add_u64 v[206:207], s[34:35], 0, v[186:187]
	s_mov_b32 m0, s62
	s_nop 0
	global_load_lds_dwordx4 v186, s[34:35]
	s_mov_b32 m0, s63
	s_nop 0
	global_load_lds_dwordx4 v190, s[34:35]
	s_waitcnt vmcnt(8)
	s_waitcnt lgkmcnt(0)
	s_barrier
	s_setprio 1
	s_waitcnt lgkmcnt(0)
	v_mfma_f32_16x16x32_bf16 v[126:129], v[10:13], v[146:149], v[126:129]
	v_mfma_f32_16x16x32_bf16 v[122:125], v[18:21], v[146:149], v[122:125]
	v_mfma_f32_16x16x32_bf16 v[110:113], v[10:13], v[162:165], v[110:113]
	v_mfma_f32_16x16x32_bf16 v[106:109], v[18:21], v[162:165], v[106:109]
	v_mfma_f32_16x16x32_bf16 v[94:97], v[10:13], v[178:181], v[94:97]
	v_mfma_f32_16x16x32_bf16 v[90:93], v[18:21], v[178:181], v[90:93]
	v_mfma_f32_16x16x32_bf16 v[10:13], v[10:13], v[198:201], v[78:81]
	v_mfma_f32_16x16x32_bf16 v[126:129], v[14:17], v[150:153], v[126:129]
	v_mfma_f32_16x16x32_bf16 v[122:125], v[22:25], v[150:153], v[122:125]
	v_mfma_f32_16x16x32_bf16 v[110:113], v[14:17], v[166:169], v[110:113]
	v_mfma_f32_16x16x32_bf16 v[106:109], v[22:25], v[166:169], v[106:109]
	v_mfma_f32_16x16x32_bf16 v[94:97], v[14:17], v[182:185], v[94:97]
	v_mfma_f32_16x16x32_bf16 v[90:93], v[22:25], v[182:185], v[90:93]
	v_mfma_f32_16x16x32_bf16 v[10:13], v[14:17], v[208:211], v[10:13]
	v_mfma_f32_16x16x32_bf16 v[14:17], v[18:21], v[198:201], v[74:77]
	v_mfma_f32_16x16x32_bf16 v[14:17], v[22:25], v[208:211], v[14:17]
	s_setprio 0
	s_setprio 1
	v_mfma_f32_16x16x32_bf16 v[74:77], v[26:29], v[162:165], v[102:105]
	v_mfma_f32_16x16x32_bf16 v[102:105], v[30:33], v[166:169], v[74:77]
	v_mfma_f32_16x16x32_bf16 v[74:77], v[42:45], v[162:165], v[98:101]
	v_mfma_f32_16x16x32_bf16 v[98:101], v[46:49], v[166:169], v[74:77]
	v_mfma_f32_16x16x32_bf16 v[74:77], v[26:29], v[178:181], v[86:89]
	v_mfma_f32_16x16x32_bf16 v[18:21], v[26:29], v[146:149], v[118:121]
	v_mfma_f32_16x16x32_bf16 v[86:89], v[30:33], v[182:185], v[74:77]
	v_mfma_f32_16x16x32_bf16 v[74:77], v[42:45], v[178:181], v[82:85]
	v_mfma_f32_16x16x32_bf16 v[26:29], v[26:29], v[198:201], v[70:73]
	v_mfma_f32_16x16x32_bf16 v[18:21], v[30:33], v[150:153], v[18:21]
	v_mfma_f32_16x16x32_bf16 v[22:25], v[42:45], v[146:149], v[114:117]
	v_mfma_f32_16x16x32_bf16 v[82:85], v[46:49], v[182:185], v[74:77]
	v_mfma_f32_16x16x32_bf16 v[26:29], v[30:33], v[208:211], v[26:29]
	v_mfma_f32_16x16x32_bf16 v[30:33], v[42:45], v[198:201], v[66:69]
	v_mfma_f32_16x16x32_bf16 v[22:25], v[46:49], v[150:153], v[22:25]
	v_mfma_f32_16x16x32_bf16 v[30:33], v[46:49], v[208:211], v[30:33]
	s_setprio 0
	s_barrier
; #define PG8_STAGE(bufoff, gbase, voff) do { _Pragma("unroll") for (int _i = 0; _i < 2; ++_i) \
;         __builtin_amdgcn_global_load_lds((const unsigned*)((const char*)(gbase) + (voff)[_i]), (LAS unsigned*)(lds + (bufoff) + ldsw + _i * 8192), 16, 0, 0); } while (0)
; #define PG8_LDA(dst, b, h) do { _Pragma("unroll") for (int m = 0; m < NM; ++m) _Pragma("unroll") for (int k = 0; k < 2; ++k) dst[m][k] = *(const LAS bf16x8*)(lds + PG8_SA(b, h) + aoff + m * 2048 + k * 1024); } while (0)
; #define PG8_LDB(dst, b, h) do { _Pragma("unroll") for (int n = 0; n < 2; ++n) _Pragma("unroll") for (int k = 0; k < 2; ++k) dst[n][k] = *(const LAS bf16x8*)(lds + PG8_SB(b, h) + boff + n * 2048 + k * 1024); } while (0)
; #define PG8_MMA(ai, bj, At, Bt) do { __builtin_amdgcn_s_setprio(1); _Pragma("unroll") for (int m = 0; m < NM; ++m) _Pragma("unroll") for (int n = 0; n < 2; ++n) _Pragma("unroll") for (int k = 0; k < 2; ++k) \
;         acc[ai][bj][m][n] = __builtin_amdgcn_mfma_f32_16x16x32_bf16(Bt[n][k], At[m][k], acc[ai][bj][m][n], 0, 0, 0); __builtin_amdgcn_s_setprio(0); } while (0)
; #define PG8_WAIT_V(n) asm volatile("s_waitcnt vmcnt(" #n ")" ::: "memory")
; #define PG8_WAIT_L(n) asm volatile("s_waitcnt lgkmcnt(" #n ")" ::: "memory")
; #define PG8_BAR __builtin_amdgcn_s_barrier()
; #define PG8_SCHED __builtin_amdgcn_sched_barrier(0)
;     ...
;             PG8_LDB(B0, 1, 0); PG8_LDB(B1, 1, 1); PG8_SCHED; PG8_LDA(At, 1, 0); PG8_STAGE(PG8_SA(0, 1), a2 + hstepA, voffA);
;             PG8_WAIT_V(8); PG8_WAIT_L(0); PG8_BAR; PG8_MMA(0, 0, At, B0); PG8_MMA(0, 1, At, B1); PG8_BAR; PG8_SCHED;
;             PG8_LDA(At, 1, 1); PG8_STAGE(PG8_SB(1, 0), b3, voffB); PG8_STAGE(PG8_SB(1, 1), b3 + hstepB, voffB); PG8_STAGE(PG8_SA(1, 0), a3, voffA);
;             PG8_WAIT_V(8); PG8_WAIT_L(0); PG8_BAR; PG8_MMA(1, 0, At, B0); PG8_MMA(1, 1, At, B1); PG8_BAR; PG8_SCHED;
	v_add_u32_e32 v0, s69, v216
	ds_read_b128 v[42:45], v0
	ds_read_b128 v[46:49], v0 offset:1024
	ds_read_b128 v[66:69], v0 offset:2048
	ds_read_b128 v[70:73], v0 offset:3072
	v_add_u32_e32 v0, s74, v216
	ds_read_b128 v[178:181], v0
	ds_read_b128 v[182:185], v0 offset:1024
	ds_read_b128 v[198:201], v0 offset:2048
	ds_read_b128 v[208:211], v0 offset:3072
	s_add_u32 s34, s34, 0x20000
	s_addc_u32 s35, s35, 0
	s_mov_b32 m0, s64
	ds_read_b128 v[74:77], v217 offset:32768
	ds_read_b128 v[78:81], v217 offset:33792
	ds_read_b128 v[114:117], v217 offset:34816
	ds_read_b128 v[118:121], v217 offset:35840
	ds_read_b128 v[146:149], v217 offset:36864
	ds_read_b128 v[212:215], v217 offset:37888
	ds_read_b128 v[218:221], v217 offset:38912
	ds_read_b128 v[226:229], v217 offset:39936
	global_load_lds_dwordx4 v186, s[34:35]
	s_mov_b32 m0, s68
	s_nop 0
	global_load_lds_dwordx4 v190, s[34:35]
	s_waitcnt vmcnt(8)
	s_waitcnt lgkmcnt(0)
	s_barrier
	s_setprio 1
	s_waitcnt lgkmcnt(0)
	v_mfma_f32_16x16x32_bf16 v[150:153], v[42:45], v[114:117], v[174:177]
	v_mfma_f32_16x16x32_bf16 v[174:177], v[46:49], v[118:121], v[150:153]
	v_mfma_f32_16x16x32_bf16 v[150:153], v[66:69], v[114:117], v[170:173]
	v_mfma_f32_16x16x32_bf16 v[170:173], v[70:73], v[118:121], v[150:153]
	v_mfma_f32_16x16x32_bf16 v[150:153], v[42:45], v[146:149], v[158:161]
	v_mfma_f32_16x16x32_bf16 v[38:41], v[42:45], v[74:77], v[38:41]
	v_mfma_f32_16x16x32_bf16 v[34:37], v[66:69], v[74:77], v[34:37]
	v_mfma_f32_16x16x32_bf16 v[158:161], v[46:49], v[212:215], v[150:153]
	v_mfma_f32_16x16x32_bf16 v[150:153], v[66:69], v[146:149], v[154:157]
	v_mfma_f32_16x16x32_bf16 v[142:145], v[42:45], v[218:221], v[142:145]
	v_mfma_f32_16x16x32_bf16 v[138:141], v[66:69], v[218:221], v[138:141]
	v_mfma_f32_16x16x32_bf16 v[38:41], v[46:49], v[78:81], v[38:41]
	v_mfma_f32_16x16x32_bf16 v[34:37], v[70:73], v[78:81], v[34:37]
	v_mfma_f32_16x16x32_bf16 v[154:157], v[70:73], v[212:215], v[150:153]
	v_mfma_f32_16x16x32_bf16 v[142:145], v[46:49], v[226:229], v[142:145]
	v_mfma_f32_16x16x32_bf16 v[138:141], v[70:73], v[226:229], v[138:141]
	s_setprio 0
	s_setprio 1
	v_mfma_f32_16x16x32_bf16 v[50:53], v[178:181], v[114:117], v[50:53]
	v_mfma_f32_16x16x32_bf16 v[166:169], v[182:185], v[118:121], v[50:53]
	v_mfma_f32_16x16x32_bf16 v[50:53], v[198:201], v[114:117], v[54:57]
	v_mfma_f32_16x16x32_bf16 v[162:165], v[208:211], v[118:121], v[50:53]
	v_mfma_f32_16x16x32_bf16 v[50:53], v[178:181], v[146:149], v[58:61]
	v_mfma_f32_16x16x32_bf16 v[150:153], v[182:185], v[212:215], v[50:53]
	v_mfma_f32_16x16x32_bf16 v[50:53], v[198:201], v[146:149], v[62:65]
	v_mfma_f32_16x16x32_bf16 v[146:149], v[208:211], v[212:215], v[50:53]
	v_mfma_f32_16x16x32_bf16 v[50:53], v[178:181], v[218:221], v[134:137]
	v_mfma_f32_16x16x32_bf16 v[6:9], v[178:181], v[74:77], v[6:9]
	v_mfma_f32_16x16x32_bf16 v[2:5], v[198:201], v[74:77], v[2:5]
	v_mfma_f32_16x16x32_bf16 v[134:137], v[182:185], v[226:229], v[50:53]
	v_mfma_f32_16x16x32_bf16 v[50:53], v[198:201], v[218:221], v[130:133]
	v_mfma_f32_16x16x32_bf16 v[6:9], v[182:185], v[78:81], v[6:9]
	v_mfma_f32_16x16x32_bf16 v[2:5], v[208:211], v[78:81], v[2:5]
	v_mfma_f32_16x16x32_bf16 v[130:133], v[208:211], v[226:229], v[50:53]
	s_setprio 0
	s_barrier
	s_mov_b32 m0, s70
	v_lshl_add_u64 v[74:75], v[202:203], 0, s[66:67]
	s_add_u32 s12, s12, 0x20080
	ds_read_b128 v[50:53], v217 offset:49152
	ds_read_b128 v[54:57], v217 offset:50176
	ds_read_b128 v[58:61], v217 offset:51200
	ds_read_b128 v[62:65], v217 offset:52224
	ds_read_b128 v[212:215], v217 offset:53248
	ds_read_b128 v[218:221], v217 offset:54272
	ds_read_b128 v[226:229], v217 offset:55296
	ds_read_b128 v[230:233], v217 offset:56320
	global_load_lds_dwordx4 v[74:75], off
	v_lshl_add_u64 v[74:75], v[204:205], 0, s[66:67]
	s_mov_b32 m0, s71
	s_addc_u32 s13, s13, 0
	global_load_lds_dwordx4 v[74:75], off
	s_mov_b32 m0, s75
	s_nop 0
	global_load_lds_dwordx4 v188, s[12:13]
	s_mov_b32 m0, s80
	s_nop 0
	global_load_lds_dwordx4 v192, s[12:13]
	v_lshl_add_u64 v[74:75], v[206:207], 0, s[66:67]
	s_mov_b32 m0, s72
	s_nop 0
	global_load_lds_dwordx4 v[74:75], off
	v_lshl_add_u64 v[74:75], v[222:223], 0, s[66:67]
	s_mov_b32 m0, s73
	s_nop 0
	global_load_lds_dwordx4 v[74:75], off
	s_waitcnt vmcnt(8)
	s_waitcnt lgkmcnt(0)
	s_barrier
	s_setprio 1
	s_waitcnt lgkmcnt(0)
	v_mfma_f32_16x16x32_bf16 v[74:77], v[42:45], v[50:53], v[126:129]
	v_mfma_f32_16x16x32_bf16 v[126:129], v[46:49], v[54:57], v[74:77]
	v_mfma_f32_16x16x32_bf16 v[74:77], v[66:69], v[50:53], v[122:125]
	v_mfma_f32_16x16x32_bf16 v[122:125], v[70:73], v[54:57], v[74:77]
	v_mfma_f32_16x16x32_bf16 v[74:77], v[42:45], v[58:61], v[110:113]
	v_mfma_f32_16x16x32_bf16 v[110:113], v[46:49], v[62:65], v[74:77]
	v_mfma_f32_16x16x32_bf16 v[74:77], v[66:69], v[58:61], v[106:109]
	v_mfma_f32_16x16x32_bf16 v[106:109], v[70:73], v[62:65], v[74:77]
	v_mfma_f32_16x16x32_bf16 v[74:77], v[42:45], v[212:215], v[94:97]
	v_mfma_f32_16x16x32_bf16 v[10:13], v[42:45], v[226:229], v[10:13]
	v_mfma_f32_16x16x32_bf16 v[94:97], v[46:49], v[218:221], v[74:77]
	v_mfma_f32_16x16x32_bf16 v[74:77], v[66:69], v[212:215], v[90:93]
	v_mfma_f32_16x16x32_bf16 v[78:81], v[46:49], v[230:233], v[10:13]
	v_mfma_f32_16x16x32_bf16 v[10:13], v[66:69], v[226:229], v[14:17]
	v_mfma_f32_16x16x32_bf16 v[90:93], v[70:73], v[218:221], v[74:77]
	v_mfma_f32_16x16x32_bf16 v[74:77], v[70:73], v[230:233], v[10:13]
	s_setprio 0
	s_setprio 1
	v_mfma_f32_16x16x32_bf16 v[10:13], v[178:181], v[50:53], v[18:21]
	v_mfma_f32_16x16x32_bf16 v[118:121], v[182:185], v[54:57], v[10:13]
	v_mfma_f32_16x16x32_bf16 v[10:13], v[198:201], v[50:53], v[22:25]
	v_mfma_f32_16x16x32_bf16 v[114:117], v[208:211], v[54:57], v[10:13]
	v_mfma_f32_16x16x32_bf16 v[10:13], v[178:181], v[58:61], v[102:105]
	v_mfma_f32_16x16x32_bf16 v[102:105], v[182:185], v[62:65], v[10:13]
	v_mfma_f32_16x16x32_bf16 v[10:13], v[198:201], v[58:61], v[98:101]
	v_mfma_f32_16x16x32_bf16 v[98:101], v[208:211], v[62:65], v[10:13]
	v_mfma_f32_16x16x32_bf16 v[10:13], v[178:181], v[212:215], v[86:89]
	v_mfma_f32_16x16x32_bf16 v[86:89], v[182:185], v[218:221], v[10:13]
	v_mfma_f32_16x16x32_bf16 v[10:13], v[198:201], v[212:215], v[82:85]
	v_mfma_f32_16x16x32_bf16 v[82:85], v[208:211], v[218:221], v[10:13]
	v_mfma_f32_16x16x32_bf16 v[10:13], v[178:181], v[226:229], v[26:29]
	v_mfma_f32_16x16x32_bf16 v[70:73], v[182:185], v[230:233], v[10:13]
	v_mfma_f32_16x16x32_bf16 v[10:13], v[198:201], v[226:229], v[30:33]
	v_mfma_f32_16x16x32_bf16 v[66:69], v[208:211], v[230:233], v[10:13]
	s_setprio 0
	s_barrier
	s_add_i32 s54, s54, 2
	s_add_u32 s10, s10, 0x100
	s_addc_u32 s11, s11, 0
	s_add_u32 s9, s9, 0x100
	s_addc_u32 s52, s52, 0
	s_cmp_gt_u32 s54, 5
	s_cbranch_scc0 .LBB0_1192
	s_and_b64 vcc, exec, s[16:17]
	s_cbranch_vccz .LBB0_1195
	s_barrier

; #define PG8_STAGE(bufoff, gbase, voff) do { _Pragma("unroll") for (int _i = 0; _i < 2; ++_i) \
;         __builtin_amdgcn_global_load_lds((const unsigned*)((const char*)(gbase) + (voff)[_i]), (LAS unsigned*)(lds + (bufoff) + ldsw + _i * 8192), 16, 0, 0); } while (0)
; #define PG8_LDA(dst, b, h) do { _Pragma("unroll") for (int m = 0; m < NM; ++m) _Pragma("unroll") for (int k = 0; k < 2; ++k) dst[m][k] = *(const LAS bf16x8*)(lds + PG8_SA(b, h) + aoff + m * 2048 + k * 1024); } while (0)
; #define PG8_LDB(dst, b, h) do { _Pragma("unroll") for (int n = 0; n < 2; ++n) _Pragma("unroll") for (int k = 0; k < 2; ++k) dst[n][k] = *(const LAS bf16x8*)(lds + PG8_SB(b, h) + boff + n * 2048 + k * 1024); } while (0)
; #define PG8_MMA(ai, bj, At, Bt) do { __builtin_amdgcn_s_setprio(1); _Pragma("unroll") for (int m = 0; m < NM; ++m) _Pragma("unroll") for (int n = 0; n < 2; ++n) _Pragma("unroll") for (int k = 0; k < 2; ++k) \
;         acc[ai][bj][m][n] = __builtin_amdgcn_mfma_f32_16x16x32_bf16(Bt[n][k], At[m][k], acc[ai][bj][m][n], 0, 0, 0); __builtin_amdgcn_s_setprio(0); } while (0)
; #define PG8_WAIT_V(n) asm volatile("s_waitcnt vmcnt(" #n ")" ::: "memory")
; #define PG8_WAIT_L(n) asm volatile("s_waitcnt lgkmcnt(" #n ")" ::: "memory")
; #define PG8_BAR __builtin_amdgcn_s_barrier()
; #define PG8_SCHED __builtin_amdgcn_sched_barrier(0)
;     ...
;         for (int t = 0; t < nt; t += 2) {
;             const bool last = (t == nt - 2);
;             const char* a1 = cA + (size_t)(t + 1) * kstep;
;             const char* a2 = last ? nA : cA + (size_t)(t + 2) * kstep; const char* b2 = last ? nB : cB + (size_t)(t + 2) * kstep;
;             const char* a3 = a2 + kstep; const char* b3 = b2 + kstep;
;             if constexpr (SP2) {
;             PG8_LDB(B0, 0, 0); PG8_LDB(B1, 0, 1); PG8_SCHED; PG8_LDA(At, 0, 0); PG8_STAGE(PG8_SA(1, 1), a1 + hstepA, voffA);
;             PG8_WAIT_V(8); PG8_WAIT_L(0); PG8_BAR; PG8_MMA(0, 0, At, B0); PG8_MMA(0, 1, At, B1); PG8_BAR; PG8_SCHED;
;             PG8_LDA(At, 0, 1); PG8_STAGE(PG8_SB(0, 0), b2, voffB); PG8_STAGE(PG8_SB(0, 1), b2 + hstepB, voffB); PG8_STAGE(PG8_SA(0, 0), a2, voffA);
;             PG8_WAIT_V(8); PG8_WAIT_L(0); PG8_BAR; PG8_MMA(1, 0, At, B0); PG8_MMA(1, 1, At, B1); PG8_BAR; PG8_SCHED;
.LBB0_1454:
	v_add_u32_e32 v140, s31, v142
	ds_read_b128 v[144:147], v140
	ds_read_b128 v[148:151], v140 offset:1024
	ds_read_b128 v[152:155], v140 offset:2048
	ds_read_b128 v[156:159], v140 offset:3072
	v_add_u32_e32 v140, s35, v142
	ds_read_b128 v[160:163], v140
	ds_read_b128 v[164:167], v140 offset:1024
	ds_read_b128 v[168:171], v140 offset:2048
	ds_read_b128 v[172:175], v140 offset:3072
	s_add_u32 s6, s20, 0x100
	s_addc_u32 s7, s21, 0
	s_cmp_eq_u32 s73, 4
	s_cselect_b32 s25, s17, s7
	s_cselect_b32 s24, s16, s6
	s_cselect_b32 s23, s2, s60
	s_cselect_b32 s22, s3, s15
	s_add_i32 m0, s45, 0xc000
	ds_read_b128 v[176:179], v143
	ds_read_b128 v[180:183], v143 offset:1024
	ds_read_b128 v[184:187], v143 offset:2048
	ds_read_b128 v[188:191], v143 offset:3072
	ds_read_b128 v[192:195], v143 offset:4096
	ds_read_b128 v[196:199], v143 offset:5120
	ds_read_b128 v[200:203], v143 offset:6144
	ds_read_b128 v[208:211], v143 offset:7168
	global_load_lds_dwordx4 v136, s[20:21]
	s_add_i32 m0, s45, 0xe000
	s_nop 0
	global_load_lds_dwordx4 v138, s[20:21]
	s_waitcnt vmcnt(8)
	s_waitcnt lgkmcnt(0)
	s_barrier
	s_setprio 1
	s_waitcnt lgkmcnt(0)
	v_mfma_f32_16x16x32_bf16 v[126:129], v[144:147], v[176:179], v[126:129]
	v_mfma_f32_16x16x32_bf16 v[122:125], v[152:155], v[176:179], v[122:125]
	v_mfma_f32_16x16x32_bf16 v[118:121], v[144:147], v[184:187], v[118:121]
	v_mfma_f32_16x16x32_bf16 v[114:117], v[152:155], v[184:187], v[114:117]
	v_mfma_f32_16x16x32_bf16 v[110:113], v[144:147], v[192:195], v[110:113]
	v_mfma_f32_16x16x32_bf16 v[106:109], v[152:155], v[192:195], v[106:109]
	v_mfma_f32_16x16x32_bf16 v[102:105], v[144:147], v[200:203], v[102:105]
	v_mfma_f32_16x16x32_bf16 v[98:101], v[152:155], v[200:203], v[98:101]
	v_mfma_f32_16x16x32_bf16 v[126:129], v[148:151], v[180:183], v[126:129]
	v_mfma_f32_16x16x32_bf16 v[122:125], v[156:159], v[180:183], v[122:125]
	v_mfma_f32_16x16x32_bf16 v[118:121], v[148:151], v[188:191], v[118:121]
	v_mfma_f32_16x16x32_bf16 v[114:117], v[156:159], v[188:191], v[114:117]
	v_mfma_f32_16x16x32_bf16 v[110:113], v[148:151], v[196:199], v[110:113]
	v_mfma_f32_16x16x32_bf16 v[106:109], v[156:159], v[196:199], v[106:109]
	v_mfma_f32_16x16x32_bf16 v[102:105], v[148:151], v[208:211], v[102:105]
	v_mfma_f32_16x16x32_bf16 v[98:101], v[156:159], v[208:211], v[98:101]
	s_setprio 0
	s_setprio 1
	v_mfma_f32_16x16x32_bf16 v[62:65], v[160:163], v[176:179], v[62:65]
	v_mfma_f32_16x16x32_bf16 v[58:61], v[168:171], v[176:179], v[58:61]
	v_mfma_f32_16x16x32_bf16 v[54:57], v[160:163], v[184:187], v[54:57]
	v_mfma_f32_16x16x32_bf16 v[50:53], v[168:171], v[184:187], v[50:53]
	v_mfma_f32_16x16x32_bf16 v[46:49], v[160:163], v[192:195], v[46:49]
	v_mfma_f32_16x16x32_bf16 v[42:45], v[168:171], v[192:195], v[42:45]
	v_mfma_f32_16x16x32_bf16 v[38:41], v[160:163], v[200:203], v[38:41]
	v_mfma_f32_16x16x32_bf16 v[34:37], v[168:171], v[200:203], v[34:37]
	v_mfma_f32_16x16x32_bf16 v[62:65], v[164:167], v[180:183], v[62:65]
	v_mfma_f32_16x16x32_bf16 v[58:61], v[172:175], v[180:183], v[58:61]
	v_mfma_f32_16x16x32_bf16 v[54:57], v[164:167], v[188:191], v[54:57]
	v_mfma_f32_16x16x32_bf16 v[50:53], v[172:175], v[188:191], v[50:53]
	v_mfma_f32_16x16x32_bf16 v[46:49], v[164:167], v[196:199], v[46:49]
	v_mfma_f32_16x16x32_bf16 v[42:45], v[172:175], v[196:199], v[42:45]
	v_mfma_f32_16x16x32_bf16 v[38:41], v[164:167], v[208:211], v[38:41]
	v_mfma_f32_16x16x32_bf16 v[34:37], v[172:175], v[208:211], v[34:37]
	s_setprio 0
	s_barrier
	s_mov_b32 m0, s33
	v_lshl_add_u64 v[140:141], s[22:23], 0, v[0:1]
	s_add_u32 s20, s22, 0x20000
	ds_read_b128 v[176:179], v143 offset:16384
	ds_read_b128 v[180:183], v143 offset:17408
	ds_read_b128 v[184:187], v143 offset:18432
	ds_read_b128 v[188:191], v143 offset:19456
	ds_read_b128 v[192:195], v143 offset:20480
	ds_read_b128 v[196:199], v143 offset:21504
	ds_read_b128 v[200:203], v143 offset:22528
	ds_read_b128 v[208:211], v143 offset:23552
	global_load_lds_dwordx4 v0, s[22:23]
	v_lshl_add_u64 v[204:205], s[22:23], 0, v[134:135]
	s_mov_b32 m0, s34
	s_addc_u32 s21, s23, 0
	global_load_lds_dwordx4 v134, s[22:23]
	s_mov_b32 m0, s43
	v_lshl_add_u64 v[212:213], s[24:25], 0, v[132:133]
	global_load_lds_dwordx4 v0, s[20:21]
	s_mov_b32 m0, s44
	s_nop 0
	global_load_lds_dwordx4 v134, s[20:21]
	v_lshl_add_u64 v[206:207], s[24:25], 0, v[130:131]
	s_mov_b32 m0, s45
	s_nop 0
	global_load_lds_dwordx4 v130, s[24:25]
	s_mov_b32 m0, s47
	s_nop 0
	global_load_lds_dwordx4 v132, s[24:25]
	s_waitcnt vmcnt(8)
	s_waitcnt lgkmcnt(0)
	s_barrier
	s_setprio 1
	s_waitcnt lgkmcnt(0)
	v_mfma_f32_16x16x32_bf16 v[94:97], v[144:147], v[176:179], v[94:97]
	v_mfma_f32_16x16x32_bf16 v[90:93], v[152:155], v[176:179], v[90:93]
	v_mfma_f32_16x16x32_bf16 v[86:89], v[144:147], v[184:187], v[86:89]
	v_mfma_f32_16x16x32_bf16 v[82:85], v[152:155], v[184:187], v[82:85]
	v_mfma_f32_16x16x32_bf16 v[78:81], v[144:147], v[192:195], v[78:81]
	v_mfma_f32_16x16x32_bf16 v[74:77], v[152:155], v[192:195], v[74:77]
	v_mfma_f32_16x16x32_bf16 v[70:73], v[144:147], v[200:203], v[70:73]
	v_mfma_f32_16x16x32_bf16 v[66:69], v[152:155], v[200:203], v[66:69]
	v_mfma_f32_16x16x32_bf16 v[94:97], v[148:151], v[180:183], v[94:97]
	v_mfma_f32_16x16x32_bf16 v[90:93], v[156:159], v[180:183], v[90:93]
	v_mfma_f32_16x16x32_bf16 v[86:89], v[148:151], v[188:191], v[86:89]
	v_mfma_f32_16x16x32_bf16 v[82:85], v[156:159], v[188:191], v[82:85]
	v_mfma_f32_16x16x32_bf16 v[78:81], v[148:151], v[196:199], v[78:81]
	v_mfma_f32_16x16x32_bf16 v[74:77], v[156:159], v[196:199], v[74:77]
	v_mfma_f32_16x16x32_bf16 v[70:73], v[148:151], v[208:211], v[70:73]
	v_mfma_f32_16x16x32_bf16 v[66:69], v[156:159], v[208:211], v[66:69]
	s_setprio 0
	s_setprio 1
	v_mfma_f32_16x16x32_bf16 v[30:33], v[160:163], v[176:179], v[30:33]
	v_mfma_f32_16x16x32_bf16 v[26:29], v[168:171], v[176:179], v[26:29]
	v_mfma_f32_16x16x32_bf16 v[22:25], v[160:163], v[184:187], v[22:25]
	v_mfma_f32_16x16x32_bf16 v[18:21], v[168:171], v[184:187], v[18:21]
	v_mfma_f32_16x16x32_bf16 v[14:17], v[160:163], v[192:195], v[14:17]
	v_mfma_f32_16x16x32_bf16 v[10:13], v[168:171], v[192:195], v[10:13]
	v_mfma_f32_16x16x32_bf16 v[6:9], v[160:163], v[200:203], v[6:9]
	v_mfma_f32_16x16x32_bf16 v[2:5], v[168:171], v[200:203], v[2:5]
	v_mfma_f32_16x16x32_bf16 v[30:33], v[164:167], v[180:183], v[30:33]
	v_mfma_f32_16x16x32_bf16 v[26:29], v[172:175], v[180:183], v[26:29]
	v_mfma_f32_16x16x32_bf16 v[22:25], v[164:167], v[188:191], v[22:25]
	v_mfma_f32_16x16x32_bf16 v[18:21], v[172:175], v[188:191], v[18:21]
	v_mfma_f32_16x16x32_bf16 v[14:17], v[164:167], v[196:199], v[14:17]
	v_mfma_f32_16x16x32_bf16 v[10:13], v[172:175], v[196:199], v[10:13]
	v_mfma_f32_16x16x32_bf16 v[6:9], v[164:167], v[208:211], v[6:9]
	v_mfma_f32_16x16x32_bf16 v[2:5], v[172:175], v[208:211], v[2:5]
	s_setprio 0
	s_barrier
; #define PG8_STAGE(bufoff, gbase, voff) do { _Pragma("unroll") for (int _i = 0; _i < 2; ++_i) \
;         __builtin_amdgcn_global_load_lds((const unsigned*)((const char*)(gbase) + (voff)[_i]), (LAS unsigned*)(lds + (bufoff) + ldsw + _i * 8192), 16, 0, 0); } while (0)
; #define PG8_LDA(dst, b, h) do { _Pragma("unroll") for (int m = 0; m < NM; ++m) _Pragma("unroll") for (int k = 0; k < 2; ++k) dst[m][k] = *(const LAS bf16x8*)(lds + PG8_SA(b, h) + aoff + m * 2048 + k * 1024); } while (0)
; #define PG8_LDB(dst, b, h) do { _Pragma("unroll") for (int n = 0; n < 2; ++n) _Pragma("unroll") for (int k = 0; k < 2; ++k) dst[n][k] = *(const LAS bf16x8*)(lds + PG8_SB(b, h) + boff + n * 2048 + k * 1024); } while (0)
; #define PG8_MMA(ai, bj, At, Bt) do { __builtin_amdgcn_s_setprio(1); _Pragma("unroll") for (int m = 0; m < NM; ++m) _Pragma("unroll") for (int n = 0; n < 2; ++n) _Pragma("unroll") for (int k = 0; k < 2; ++k) \
;         acc[ai][bj][m][n] = __builtin_amdgcn_mfma_f32_16x16x32_bf16(Bt[n][k], At[m][k], acc[ai][bj][m][n], 0, 0, 0); __builtin_amdgcn_s_setprio(0); } while (0)
; #define PG8_WAIT_V(n) asm volatile("s_waitcnt vmcnt(" #n ")" ::: "memory")
; #define PG8_WAIT_L(n) asm volatile("s_waitcnt lgkmcnt(" #n ")" ::: "memory")
; #define PG8_BAR __builtin_amdgcn_s_barrier()
; #define PG8_SCHED __builtin_amdgcn_sched_barrier(0)
;     ...
;             PG8_LDB(B0, 1, 0); PG8_LDB(B1, 1, 1); PG8_SCHED; PG8_LDA(At, 1, 0); PG8_STAGE(PG8_SA(0, 1), a2 + hstepA, voffA);
;             PG8_WAIT_V(8); PG8_WAIT_L(0); PG8_BAR; PG8_MMA(0, 0, At, B0); PG8_MMA(0, 1, At, B1); PG8_BAR; PG8_SCHED;
;             PG8_LDA(At, 1, 1); PG8_STAGE(PG8_SB(1, 0), b3, voffB); PG8_STAGE(PG8_SB(1, 1), b3 + hstepB, voffB); PG8_STAGE(PG8_SA(1, 0), a3, voffA);
;             PG8_WAIT_V(8); PG8_WAIT_L(0); PG8_BAR; PG8_MMA(1, 0, At, B0); PG8_MMA(1, 1, At, B1); PG8_BAR; PG8_SCHED;
	v_add_u32_e32 v156, s50, v142
	v_add_u32_e32 v172, s57, v142
	ds_read_b128 v[144:147], v156
	ds_read_b128 v[148:151], v156 offset:1024
	ds_read_b128 v[152:155], v156 offset:2048
	ds_read_b128 v[156:159], v156 offset:3072
	ds_read_b128 v[160:163], v172
	ds_read_b128 v[164:167], v172 offset:1024
	ds_read_b128 v[168:171], v172 offset:2048
	ds_read_b128 v[172:175], v172 offset:3072
	s_add_u32 s20, s24, 0x24000
	s_addc_u32 s21, s25, 0
	s_mov_b32 m0, s48
	ds_read_b128 v[176:179], v143 offset:32768
	ds_read_b128 v[180:183], v143 offset:33792
	ds_read_b128 v[184:187], v143 offset:34816
	ds_read_b128 v[188:191], v143 offset:35840
	ds_read_b128 v[192:195], v143 offset:36864
	ds_read_b128 v[196:199], v143 offset:37888
	ds_read_b128 v[200:203], v143 offset:38912
	ds_read_b128 v[208:211], v143 offset:39936
	global_load_lds_dwordx4 v130, s[20:21]
	s_mov_b32 m0, s49
	s_nop 0
	global_load_lds_dwordx4 v132, s[20:21]
	s_waitcnt vmcnt(8)
	s_waitcnt lgkmcnt(0)
	s_barrier
	s_setprio 1
	s_waitcnt lgkmcnt(0)
	v_mfma_f32_16x16x32_bf16 v[126:129], v[144:147], v[176:179], v[126:129]
	v_mfma_f32_16x16x32_bf16 v[122:125], v[152:155], v[176:179], v[122:125]
	v_mfma_f32_16x16x32_bf16 v[118:121], v[144:147], v[184:187], v[118:121]
	v_mfma_f32_16x16x32_bf16 v[114:117], v[152:155], v[184:187], v[114:117]
	v_mfma_f32_16x16x32_bf16 v[110:113], v[144:147], v[192:195], v[110:113]
	v_mfma_f32_16x16x32_bf16 v[106:109], v[152:155], v[192:195], v[106:109]
	v_mfma_f32_16x16x32_bf16 v[102:105], v[144:147], v[200:203], v[102:105]
	v_mfma_f32_16x16x32_bf16 v[98:101], v[152:155], v[200:203], v[98:101]
	v_mfma_f32_16x16x32_bf16 v[126:129], v[148:151], v[180:183], v[126:129]
	v_mfma_f32_16x16x32_bf16 v[122:125], v[156:159], v[180:183], v[122:125]
	v_mfma_f32_16x16x32_bf16 v[118:121], v[148:151], v[188:191], v[118:121]
	v_mfma_f32_16x16x32_bf16 v[114:117], v[156:159], v[188:191], v[114:117]
	v_mfma_f32_16x16x32_bf16 v[110:113], v[148:151], v[196:199], v[110:113]
	v_mfma_f32_16x16x32_bf16 v[106:109], v[156:159], v[196:199], v[106:109]
	v_mfma_f32_16x16x32_bf16 v[102:105], v[148:151], v[208:211], v[102:105]
	v_mfma_f32_16x16x32_bf16 v[98:101], v[156:159], v[208:211], v[98:101]
	s_setprio 0
	s_setprio 1
	v_mfma_f32_16x16x32_bf16 v[62:65], v[160:163], v[176:179], v[62:65]
	v_mfma_f32_16x16x32_bf16 v[58:61], v[168:171], v[176:179], v[58:61]
	v_mfma_f32_16x16x32_bf16 v[54:57], v[160:163], v[184:187], v[54:57]
	v_mfma_f32_16x16x32_bf16 v[50:53], v[168:171], v[184:187], v[50:53]
	v_mfma_f32_16x16x32_bf16 v[46:49], v[160:163], v[192:195], v[46:49]
	v_mfma_f32_16x16x32_bf16 v[42:45], v[168:171], v[192:195], v[42:45]
	v_mfma_f32_16x16x32_bf16 v[38:41], v[160:163], v[200:203], v[38:41]
	v_mfma_f32_16x16x32_bf16 v[34:37], v[168:171], v[200:203], v[34:37]
	v_mfma_f32_16x16x32_bf16 v[62:65], v[164:167], v[180:183], v[62:65]
	v_mfma_f32_16x16x32_bf16 v[58:61], v[172:175], v[180:183], v[58:61]
	v_mfma_f32_16x16x32_bf16 v[54:57], v[164:167], v[188:191], v[54:57]
	v_mfma_f32_16x16x32_bf16 v[50:53], v[172:175], v[188:191], v[50:53]
	v_mfma_f32_16x16x32_bf16 v[46:49], v[164:167], v[196:199], v[46:49]
	v_mfma_f32_16x16x32_bf16 v[42:45], v[172:175], v[196:199], v[42:45]
	v_mfma_f32_16x16x32_bf16 v[38:41], v[164:167], v[208:211], v[38:41]
	v_mfma_f32_16x16x32_bf16 v[34:37], v[172:175], v[208:211], v[34:37]
	s_setprio 0
	s_barrier
	s_mov_b32 m0, s51
	v_lshl_add_u64 v[140:141], v[140:141], 0, s[66:67]
	s_add_u32 s20, s22, 0x20080
	ds_read_b128 v[176:179], v143 offset:49152
	ds_read_b128 v[180:183], v143 offset:50176
	ds_read_b128 v[184:187], v143 offset:51200
	ds_read_b128 v[188:191], v143 offset:52224
	ds_read_b128 v[192:195], v143 offset:53248
	ds_read_b128 v[196:199], v143 offset:54272
	ds_read_b128 v[200:203], v143 offset:55296
	ds_read_b128 v[208:211], v143 offset:56320
	global_load_lds_dwordx4 v[140:141], off
	v_lshl_add_u64 v[140:141], v[204:205], 0, s[66:67]
	s_mov_b32 m0, s52
	s_addc_u32 s21, s23, 0
	global_load_lds_dwordx4 v[140:141], off
	s_mov_b32 m0, s58
	s_nop 0
	global_load_lds_dwordx4 v0, s[20:21]
	s_mov_b32 m0, s59
	s_nop 0
	global_load_lds_dwordx4 v134, s[20:21]
	v_lshl_add_u64 v[140:141], v[206:207], 0, s[66:67]
	s_mov_b32 m0, s54
	s_nop 0
	global_load_lds_dwordx4 v[140:141], off
	v_lshl_add_u64 v[140:141], v[212:213], 0, s[66:67]
	s_mov_b32 m0, s56
	s_nop 0
	global_load_lds_dwordx4 v[140:141], off
	s_waitcnt vmcnt(8)
	s_waitcnt lgkmcnt(0)
	s_barrier
	s_setprio 1
	s_waitcnt lgkmcnt(0)
	v_mfma_f32_16x16x32_bf16 v[94:97], v[144:147], v[176:179], v[94:97]
	v_mfma_f32_16x16x32_bf16 v[90:93], v[152:155], v[176:179], v[90:93]
	v_mfma_f32_16x16x32_bf16 v[86:89], v[144:147], v[184:187], v[86:89]
	v_mfma_f32_16x16x32_bf16 v[82:85], v[152:155], v[184:187], v[82:85]
	v_mfma_f32_16x16x32_bf16 v[78:81], v[144:147], v[192:195], v[78:81]
	v_mfma_f32_16x16x32_bf16 v[74:77], v[152:155], v[192:195], v[74:77]
	v_mfma_f32_16x16x32_bf16 v[70:73], v[144:147], v[200:203], v[70:73]
	v_mfma_f32_16x16x32_bf16 v[66:69], v[152:155], v[200:203], v[66:69]
	v_mfma_f32_16x16x32_bf16 v[94:97], v[148:151], v[180:183], v[94:97]
	v_mfma_f32_16x16x32_bf16 v[90:93], v[156:159], v[180:183], v[90:93]
	v_mfma_f32_16x16x32_bf16 v[86:89], v[148:151], v[188:191], v[86:89]
	v_mfma_f32_16x16x32_bf16 v[82:85], v[156:159], v[188:191], v[82:85]
	v_mfma_f32_16x16x32_bf16 v[78:81], v[148:151], v[196:199], v[78:81]
	v_mfma_f32_16x16x32_bf16 v[74:77], v[156:159], v[196:199], v[74:77]
	v_mfma_f32_16x16x32_bf16 v[70:73], v[148:151], v[208:211], v[70:73]
	v_mfma_f32_16x16x32_bf16 v[66:69], v[156:159], v[208:211], v[66:69]
	s_setprio 0
	s_setprio 1
	v_mfma_f32_16x16x32_bf16 v[30:33], v[160:163], v[176:179], v[30:33]
	v_mfma_f32_16x16x32_bf16 v[26:29], v[168:171], v[176:179], v[26:29]
	v_mfma_f32_16x16x32_bf16 v[22:25], v[160:163], v[184:187], v[22:25]
	v_mfma_f32_16x16x32_bf16 v[18:21], v[168:171], v[184:187], v[18:21]
	v_mfma_f32_16x16x32_bf16 v[14:17], v[160:163], v[192:195], v[14:17]
	v_mfma_f32_16x16x32_bf16 v[10:13], v[168:171], v[192:195], v[10:13]
	v_mfma_f32_16x16x32_bf16 v[6:9], v[160:163], v[200:203], v[6:9]
	v_mfma_f32_16x16x32_bf16 v[2:5], v[168:171], v[200:203], v[2:5]
	v_mfma_f32_16x16x32_bf16 v[30:33], v[164:167], v[180:183], v[30:33]
	v_mfma_f32_16x16x32_bf16 v[26:29], v[172:175], v[180:183], v[26:29]
	v_mfma_f32_16x16x32_bf16 v[22:25], v[164:167], v[188:191], v[22:25]
	v_mfma_f32_16x16x32_bf16 v[18:21], v[172:175], v[188:191], v[18:21]
	v_mfma_f32_16x16x32_bf16 v[14:17], v[164:167], v[196:199], v[14:17]
	v_mfma_f32_16x16x32_bf16 v[10:13], v[172:175], v[196:199], v[10:13]
	v_mfma_f32_16x16x32_bf16 v[6:9], v[164:167], v[208:211], v[6:9]
	v_mfma_f32_16x16x32_bf16 v[2:5], v[172:175], v[208:211], v[2:5]
	s_setprio 0
	s_barrier
	s_add_i32 s73, s73, 2
	s_add_u32 s15, s15, 0x100
	s_addc_u32 s60, s60, 0
	s_cmp_gt_u32 s73, 5
	s_mov_b64 s[20:21], s[6:7]
	s_cbranch_scc0 .LBB0_1454
	s_and_b64 vcc, exec, s[12:13]
	s_cbranch_vccz .LBB0_1457
	s_barrier

; #define PG8_STAGE(bufoff, gbase, voff) do { _Pragma("unroll") for (int _i = 0; _i < 2; ++_i) \
;         __builtin_amdgcn_global_load_lds((const unsigned*)((const char*)(gbase) + (voff)[_i]), (LAS unsigned*)(lds + (bufoff) + ldsw + _i * 8192), 16, 0, 0); } while (0)
; #define PG8_LDA(dst, b, h) do { _Pragma("unroll") for (int m = 0; m < NM; ++m) _Pragma("unroll") for (int k = 0; k < 2; ++k) dst[m][k] = *(const LAS bf16x8*)(lds + PG8_SA(b, h) + aoff + m * 2048 + k * 1024); } while (0)
; #define PG8_LDB(dst, b, h) do { _Pragma("unroll") for (int n = 0; n < 2; ++n) _Pragma("unroll") for (int k = 0; k < 2; ++k) dst[n][k] = *(const LAS bf16x8*)(lds + PG8_SB(b, h) + boff + n * 2048 + k * 1024); } while (0)
; #define PG8_SCHED __builtin_amdgcn_sched_barrier(0)
;     ...
;         for (int t = 0; t < nt; t += 2) {
;             const bool last = (t == nt - 2);
;             const char* a1 = cA + (size_t)(t + 1) * kstep;
;             const char* a2 = last ? nA : cA + (size_t)(t + 2) * kstep; const char* b2 = last ? nB : cB + (size_t)(t + 2) * kstep;
;             const char* a3 = a2 + kstep; const char* b3 = b2 + kstep;
;             if constexpr (SP2) {
;             PG8_LDB(B0, 0, 0); PG8_LDB(B1, 0, 1); PG8_SCHED; PG8_LDA(At, 0, 0); PG8_STAGE(PG8_SA(1, 1), a1 + hstepA, voffA);
.LBB0_1650:
	v_add_u32_e32 v102, s21, v166
	v_add_u32_e32 v126, s31, v166
	ds_read_b128 v[90:93], v102
	ds_read_b128 v[94:97], v102 offset:1024
	ds_read_b128 v[98:101], v102 offset:2048
	ds_read_b128 v[102:105], v102 offset:3072
	ds_read_b128 v[114:117], v126
	ds_read_b128 v[118:121], v126 offset:1024
	ds_read_b128 v[122:125], v126 offset:2048
	ds_read_b128 v[126:129], v126 offset:3072
	s_add_u32 s22, s8, 0xfffa0080
	s_addc_u32 s23, s9, -1
	s_cmp_eq_u32 s59, 28
	s_cselect_b32 s25, s17, s23
	s_cselect_b32 s24, s16, s22
	s_cselect_b32 s23, s2, s58
	s_cselect_b32 s22, s3, s15
	s_add_i32 m0, s35, 0xc000
	ds_read_b128 v[130:133], v167
	ds_read_b128 v[134:137], v167 offset:1024
	ds_read_b128 v[138:141], v167 offset:2048
	ds_read_b128 v[152:155], v167 offset:3072
	ds_read_b128 v[156:159], v167 offset:4096
	ds_read_b128 v[160:163], v167 offset:5120
	global_load_lds_dwordx4 v148, s[8:9]
	s_add_i32 m0, s35, 0xe000
	s_nop 0
	s_and_b64 vcc, exec, s[10:11]
	s_cbranch_vccz .Lnm3o_skip0
	global_load_lds_dwordx4 v150, s[8:9]
	s_waitcnt vmcnt(8)
	s_branch .Lnm3o_done0

; #define PG8_STAGE(bufoff, gbase, voff) do { _Pragma("unroll") for (int _i = 0; _i < 2; ++_i) \
;         __builtin_amdgcn_global_load_lds((const unsigned*)((const char*)(gbase) + (voff)[_i]), (LAS unsigned*)(lds + (bufoff) + ldsw + _i * 8192), 16, 0, 0); } while (0)
; #define PG8_LDA(dst, b, h) do { _Pragma("unroll") for (int m = 0; m < NM; ++m) _Pragma("unroll") for (int k = 0; k < 2; ++k) dst[m][k] = *(const LAS bf16x8*)(lds + PG8_SA(b, h) + aoff + m * 2048 + k * 1024); } while (0)
; #define PG8_MMA(ai, bj, At, Bt) do { __builtin_amdgcn_s_setprio(1); _Pragma("unroll") for (int m = 0; m < NM; ++m) _Pragma("unroll") for (int n = 0; n < 2; ++n) _Pragma("unroll") for (int k = 0; k < 2; ++k) \
;         acc[ai][bj][m][n] = __builtin_amdgcn_mfma_f32_16x16x32_bf16(Bt[n][k], At[m][k], acc[ai][bj][m][n], 0, 0, 0); __builtin_amdgcn_s_setprio(0); } while (0)
; #define PG8_WAIT_V(n) asm volatile("s_waitcnt vmcnt(" #n ")" ::: "memory")
; #define PG8_WAIT_L(n) asm volatile("s_waitcnt lgkmcnt(" #n ")" ::: "memory")
; #define PG8_BAR __builtin_amdgcn_s_barrier()
; #define PG8_SCHED __builtin_amdgcn_sched_barrier(0)
;     ...
;             PG8_WAIT_V(8); PG8_WAIT_L(0); PG8_BAR; PG8_MMA(0, 0, At, B0); PG8_MMA(0, 1, At, B1); PG8_BAR; PG8_SCHED;
;             PG8_LDA(At, 0, 1); PG8_STAGE(PG8_SB(0, 0), b2, voffB); PG8_STAGE(PG8_SB(0, 1), b2 + hstepB, voffB); PG8_STAGE(PG8_SA(0, 0), a2, voffA);
.Lnm3o_done0:
	s_waitcnt lgkmcnt(0)
	s_barrier
	s_setprio 1
	s_waitcnt lgkmcnt(0)
	v_mfma_f32_16x16x32_bf16 v[110:113], v[90:93], v[130:133], v[110:113]
	v_mfma_f32_16x16x32_bf16 v[106:109], v[98:101], v[130:133], v[106:109]
	v_mfma_f32_16x16x32_bf16 v[78:81], v[90:93], v[138:141], v[78:81]
	v_mfma_f32_16x16x32_bf16 v[74:77], v[98:101], v[138:141], v[74:77]
	v_mfma_f32_16x16x32_bf16 v[62:65], v[90:93], v[156:159], v[62:65]
	v_mfma_f32_16x16x32_bf16 v[58:61], v[98:101], v[156:159], v[58:61]
	v_mfma_f32_16x16x32_bf16 v[110:113], v[94:97], v[134:137], v[110:113]
	v_mfma_f32_16x16x32_bf16 v[106:109], v[102:105], v[134:137], v[106:109]
	v_mfma_f32_16x16x32_bf16 v[78:81], v[94:97], v[152:155], v[78:81]
	v_mfma_f32_16x16x32_bf16 v[74:77], v[102:105], v[152:155], v[74:77]
	v_mfma_f32_16x16x32_bf16 v[62:65], v[94:97], v[160:163], v[62:65]
	v_mfma_f32_16x16x32_bf16 v[58:61], v[102:105], v[160:163], v[58:61]
	s_setprio 0
	s_setprio 1
	v_mfma_f32_16x16x32_bf16 v[86:89], v[114:117], v[130:133], v[86:89]
	v_mfma_f32_16x16x32_bf16 v[82:85], v[122:125], v[130:133], v[82:85]
	v_mfma_f32_16x16x32_bf16 v[70:73], v[114:117], v[138:141], v[70:73]
	v_mfma_f32_16x16x32_bf16 v[66:69], v[122:125], v[138:141], v[66:69]
	v_mfma_f32_16x16x32_bf16 v[54:57], v[114:117], v[156:159], v[54:57]
	v_mfma_f32_16x16x32_bf16 v[50:53], v[122:125], v[156:159], v[50:53]
	v_mfma_f32_16x16x32_bf16 v[86:89], v[118:121], v[134:137], v[86:89]
	v_mfma_f32_16x16x32_bf16 v[82:85], v[126:129], v[134:137], v[82:85]
	v_mfma_f32_16x16x32_bf16 v[70:73], v[118:121], v[152:155], v[70:73]
	v_mfma_f32_16x16x32_bf16 v[66:69], v[126:129], v[152:155], v[66:69]
	v_mfma_f32_16x16x32_bf16 v[54:57], v[118:121], v[160:163], v[54:57]
	v_mfma_f32_16x16x32_bf16 v[50:53], v[126:129], v[160:163], v[50:53]
	s_setprio 0
	s_barrier
	s_mov_b32 m0, s29
	v_lshl_add_u64 v[164:165], s[22:23], 0, v[0:1]
	s_add_u32 s62, s22, 0x80000
	ds_read_b128 v[130:133], v167 offset:16384
	ds_read_b128 v[134:137], v167 offset:17408
	ds_read_b128 v[138:141], v167 offset:18432
	ds_read_b128 v[152:155], v167 offset:19456
	ds_read_b128 v[156:159], v167 offset:20480
	ds_read_b128 v[160:163], v167 offset:21504
	global_load_lds_dwordx4 v0, s[22:23]
	v_lshl_add_u64 v[168:169], s[22:23], 0, v[146:147]
	s_mov_b32 m0, s30
	s_addc_u32 s63, s23, 0
	global_load_lds_dwordx4 v146, s[22:23]
	s_mov_b32 m0, s33
	v_lshl_add_u64 v[172:173], s[24:25], 0, v[144:145]
	global_load_lds_dwordx4 v0, s[62:63]
	s_mov_b32 m0, s34
	s_nop 0
	global_load_lds_dwordx4 v146, s[62:63]
	v_lshl_add_u64 v[170:171], s[24:25], 0, v[142:143]
	s_mov_b32 m0, s35
	s_nop 0
	global_load_lds_dwordx4 v142, s[24:25]
	s_mov_b32 m0, s36
	s_nop 0
	s_and_b64 vcc, exec, s[10:11]
	s_cbranch_vccz .Lnm3o_skip1
	global_load_lds_dwordx4 v144, s[24:25]
	s_waitcnt vmcnt(8)
	s_branch .Lnm3o_done1

; #define PG8_STAGE(bufoff, gbase, voff) do { _Pragma("unroll") for (int _i = 0; _i < 2; ++_i) \
;         __builtin_amdgcn_global_load_lds((const unsigned*)((const char*)(gbase) + (voff)[_i]), (LAS unsigned*)(lds + (bufoff) + ldsw + _i * 8192), 16, 0, 0); } while (0)
; #define PG8_LDA(dst, b, h) do { _Pragma("unroll") for (int m = 0; m < NM; ++m) _Pragma("unroll") for (int k = 0; k < 2; ++k) dst[m][k] = *(const LAS bf16x8*)(lds + PG8_SA(b, h) + aoff + m * 2048 + k * 1024); } while (0)
; #define PG8_LDB(dst, b, h) do { _Pragma("unroll") for (int n = 0; n < 2; ++n) _Pragma("unroll") for (int k = 0; k < 2; ++k) dst[n][k] = *(const LAS bf16x8*)(lds + PG8_SB(b, h) + boff + n * 2048 + k * 1024); } while (0)
; #define PG8_MMA(ai, bj, At, Bt) do { __builtin_amdgcn_s_setprio(1); _Pragma("unroll") for (int m = 0; m < NM; ++m) _Pragma("unroll") for (int n = 0; n < 2; ++n) _Pragma("unroll") for (int k = 0; k < 2; ++k) \
;         acc[ai][bj][m][n] = __builtin_amdgcn_mfma_f32_16x16x32_bf16(Bt[n][k], At[m][k], acc[ai][bj][m][n], 0, 0, 0); __builtin_amdgcn_s_setprio(0); } while (0)
; #define PG8_WAIT_V(n) asm volatile("s_waitcnt vmcnt(" #n ")" ::: "memory")
; #define PG8_WAIT_L(n) asm volatile("s_waitcnt lgkmcnt(" #n ")" ::: "memory")
; #define PG8_BAR __builtin_amdgcn_s_barrier()
; #define PG8_SCHED __builtin_amdgcn_sched_barrier(0)
;     ...
;             PG8_WAIT_V(8); PG8_WAIT_L(0); PG8_BAR; PG8_MMA(1, 0, At, B0); PG8_MMA(1, 1, At, B1); PG8_BAR; PG8_SCHED;
;             PG8_LDB(B0, 1, 0); PG8_LDB(B1, 1, 1); PG8_SCHED; PG8_LDA(At, 1, 0); PG8_STAGE(PG8_SA(0, 1), a2 + hstepA, voffA);
.Lnm3o_done1:
	s_waitcnt lgkmcnt(0)
	s_barrier
	s_setprio 1
	s_waitcnt lgkmcnt(0)
	v_mfma_f32_16x16x32_bf16 v[46:49], v[90:93], v[130:133], v[46:49]
	v_mfma_f32_16x16x32_bf16 v[42:45], v[98:101], v[130:133], v[42:45]
	v_mfma_f32_16x16x32_bf16 v[30:33], v[90:93], v[138:141], v[30:33]
	v_mfma_f32_16x16x32_bf16 v[26:29], v[98:101], v[138:141], v[26:29]
	v_mfma_f32_16x16x32_bf16 v[14:17], v[90:93], v[156:159], v[14:17]
	v_mfma_f32_16x16x32_bf16 v[10:13], v[98:101], v[156:159], v[10:13]
	v_mfma_f32_16x16x32_bf16 v[46:49], v[94:97], v[134:137], v[46:49]
	v_mfma_f32_16x16x32_bf16 v[42:45], v[102:105], v[134:137], v[42:45]
	v_mfma_f32_16x16x32_bf16 v[30:33], v[94:97], v[152:155], v[30:33]
	v_mfma_f32_16x16x32_bf16 v[26:29], v[102:105], v[152:155], v[26:29]
	v_mfma_f32_16x16x32_bf16 v[14:17], v[94:97], v[160:163], v[14:17]
	v_mfma_f32_16x16x32_bf16 v[10:13], v[102:105], v[160:163], v[10:13]
	s_setprio 0
	s_setprio 1
	v_mfma_f32_16x16x32_bf16 v[38:41], v[114:117], v[130:133], v[38:41]
	v_mfma_f32_16x16x32_bf16 v[34:37], v[122:125], v[130:133], v[34:37]
	v_mfma_f32_16x16x32_bf16 v[22:25], v[114:117], v[138:141], v[22:25]
	v_mfma_f32_16x16x32_bf16 v[18:21], v[122:125], v[138:141], v[18:21]
	v_mfma_f32_16x16x32_bf16 v[6:9], v[114:117], v[156:159], v[6:9]
	v_mfma_f32_16x16x32_bf16 v[2:5], v[122:125], v[156:159], v[2:5]
	v_mfma_f32_16x16x32_bf16 v[38:41], v[118:121], v[134:137], v[38:41]
	v_mfma_f32_16x16x32_bf16 v[34:37], v[126:129], v[134:137], v[34:37]
	v_mfma_f32_16x16x32_bf16 v[22:25], v[118:121], v[152:155], v[22:25]
	v_mfma_f32_16x16x32_bf16 v[18:21], v[126:129], v[152:155], v[18:21]
	v_mfma_f32_16x16x32_bf16 v[6:9], v[118:121], v[160:163], v[6:9]
	v_mfma_f32_16x16x32_bf16 v[2:5], v[126:129], v[160:163], v[2:5]
	s_setprio 0
	s_barrier
	v_add_u32_e32 v102, s40, v166
	v_add_u32_e32 v126, s45, v166
	ds_read_b128 v[90:93], v102
	ds_read_b128 v[94:97], v102 offset:1024
	ds_read_b128 v[98:101], v102 offset:2048
	ds_read_b128 v[102:105], v102 offset:3072
	ds_read_b128 v[114:117], v126
	ds_read_b128 v[118:121], v126 offset:1024
	ds_read_b128 v[122:125], v126 offset:2048
	ds_read_b128 v[126:129], v126 offset:3072
	s_add_u32 s24, s24, 0x60000
	s_addc_u32 s25, s25, 0
	s_mov_b32 m0, s37
	ds_read_b128 v[130:133], v167 offset:32768
	ds_read_b128 v[134:137], v167 offset:33792
	ds_read_b128 v[138:141], v167 offset:34816
	ds_read_b128 v[152:155], v167 offset:35840
	ds_read_b128 v[156:159], v167 offset:36864
	ds_read_b128 v[160:163], v167 offset:37888
	global_load_lds_dwordx4 v142, s[24:25]
	s_mov_b32 m0, s38
	s_nop 0
	s_and_b64 vcc, exec, s[10:11]
	s_cbranch_vccz .Lnm3o_skip2
	global_load_lds_dwordx4 v144, s[24:25]
	s_waitcnt vmcnt(8)
	s_branch .Lnm3o_done2

; #define PG8_STAGE(bufoff, gbase, voff) do { _Pragma("unroll") for (int _i = 0; _i < 2; ++_i) \
;         __builtin_amdgcn_global_load_lds((const unsigned*)((const char*)(gbase) + (voff)[_i]), (LAS unsigned*)(lds + (bufoff) + ldsw + _i * 8192), 16, 0, 0); } while (0)
; #define PG8_LDA(dst, b, h) do { _Pragma("unroll") for (int m = 0; m < NM; ++m) _Pragma("unroll") for (int k = 0; k < 2; ++k) dst[m][k] = *(const LAS bf16x8*)(lds + PG8_SA(b, h) + aoff + m * 2048 + k * 1024); } while (0)
; #define PG8_MMA(ai, bj, At, Bt) do { __builtin_amdgcn_s_setprio(1); _Pragma("unroll") for (int m = 0; m < NM; ++m) _Pragma("unroll") for (int n = 0; n < 2; ++n) _Pragma("unroll") for (int k = 0; k < 2; ++k) \
;         acc[ai][bj][m][n] = __builtin_amdgcn_mfma_f32_16x16x32_bf16(Bt[n][k], At[m][k], acc[ai][bj][m][n], 0, 0, 0); __builtin_amdgcn_s_setprio(0); } while (0)
; #define PG8_WAIT_V(n) asm volatile("s_waitcnt vmcnt(" #n ")" ::: "memory")
; #define PG8_WAIT_L(n) asm volatile("s_waitcnt lgkmcnt(" #n ")" ::: "memory")
; #define PG8_BAR __builtin_amdgcn_s_barrier()
; #define PG8_SCHED __builtin_amdgcn_sched_barrier(0)
;     ...
;             PG8_WAIT_V(8); PG8_WAIT_L(0); PG8_BAR; PG8_MMA(0, 0, At, B0); PG8_MMA(0, 1, At, B1); PG8_BAR; PG8_SCHED;
;             PG8_LDA(At, 1, 1); PG8_STAGE(PG8_SB(1, 0), b3, voffB); PG8_STAGE(PG8_SB(1, 1), b3 + hstepB, voffB); PG8_STAGE(PG8_SA(1, 0), a3, voffA);
.Lnm3o_done2:
	s_waitcnt lgkmcnt(0)
	s_barrier
	s_setprio 1
	s_waitcnt lgkmcnt(0)
	v_mfma_f32_16x16x32_bf16 v[110:113], v[90:93], v[130:133], v[110:113]
	v_mfma_f32_16x16x32_bf16 v[106:109], v[98:101], v[130:133], v[106:109]
	v_mfma_f32_16x16x32_bf16 v[78:81], v[90:93], v[138:141], v[78:81]
	v_mfma_f32_16x16x32_bf16 v[74:77], v[98:101], v[138:141], v[74:77]
	v_mfma_f32_16x16x32_bf16 v[62:65], v[90:93], v[156:159], v[62:65]
	v_mfma_f32_16x16x32_bf16 v[58:61], v[98:101], v[156:159], v[58:61]
	v_mfma_f32_16x16x32_bf16 v[110:113], v[94:97], v[134:137], v[110:113]
	v_mfma_f32_16x16x32_bf16 v[106:109], v[102:105], v[134:137], v[106:109]
	v_mfma_f32_16x16x32_bf16 v[78:81], v[94:97], v[152:155], v[78:81]
	v_mfma_f32_16x16x32_bf16 v[74:77], v[102:105], v[152:155], v[74:77]
	v_mfma_f32_16x16x32_bf16 v[62:65], v[94:97], v[160:163], v[62:65]
	v_mfma_f32_16x16x32_bf16 v[58:61], v[102:105], v[160:163], v[58:61]
	s_setprio 0
	s_setprio 1
	v_mfma_f32_16x16x32_bf16 v[86:89], v[114:117], v[130:133], v[86:89]
	v_mfma_f32_16x16x32_bf16 v[82:85], v[122:125], v[130:133], v[82:85]
	v_mfma_f32_16x16x32_bf16 v[70:73], v[114:117], v[138:141], v[70:73]
	v_mfma_f32_16x16x32_bf16 v[66:69], v[122:125], v[138:141], v[66:69]
	v_mfma_f32_16x16x32_bf16 v[54:57], v[114:117], v[156:159], v[54:57]
	v_mfma_f32_16x16x32_bf16 v[50:53], v[122:125], v[156:159], v[50:53]
	v_mfma_f32_16x16x32_bf16 v[86:89], v[118:121], v[134:137], v[86:89]
	v_mfma_f32_16x16x32_bf16 v[82:85], v[126:129], v[134:137], v[82:85]
	v_mfma_f32_16x16x32_bf16 v[70:73], v[118:121], v[152:155], v[70:73]
	v_mfma_f32_16x16x32_bf16 v[66:69], v[126:129], v[152:155], v[66:69]
	v_mfma_f32_16x16x32_bf16 v[54:57], v[118:121], v[160:163], v[54:57]
	v_mfma_f32_16x16x32_bf16 v[50:53], v[126:129], v[160:163], v[50:53]
	s_setprio 0
	s_barrier
	s_mov_b32 m0, s41
	v_lshl_add_u64 v[164:165], v[164:165], 0, s[66:67]
	s_add_u32 s22, s22, 0x80080
	ds_read_b128 v[130:133], v167 offset:49152
	ds_read_b128 v[134:137], v167 offset:50176
	ds_read_b128 v[138:141], v167 offset:51200
	ds_read_b128 v[152:155], v167 offset:52224
	ds_read_b128 v[156:159], v167 offset:53248
	ds_read_b128 v[160:163], v167 offset:54272
	global_load_lds_dwordx4 v[164:165], off
	v_lshl_add_u64 v[164:165], v[168:169], 0, s[66:67]
	s_mov_b32 m0, s42
	s_addc_u32 s23, s23, 0
	global_load_lds_dwordx4 v[164:165], off
	s_mov_b32 m0, s46
	s_nop 0
	global_load_lds_dwordx4 v0, s[22:23]
	s_mov_b32 m0, s47
	s_nop 0
	global_load_lds_dwordx4 v146, s[22:23]
	v_lshl_add_u64 v[164:165], v[170:171], 0, s[66:67]
	s_mov_b32 m0, s43
	s_nop 0
	global_load_lds_dwordx4 v[164:165], off
	v_lshl_add_u64 v[164:165], v[172:173], 0, s[66:67]
	s_mov_b32 m0, s44
	s_nop 0
	s_and_b64 vcc, exec, s[10:11]
	s_cbranch_vccz .Lnm3o_skip3
	global_load_lds_dwordx4 v[164:165], off
	s_waitcnt vmcnt(8)
	s_branch .Lnm3o_done3

; #define PG8_STAGE(bufoff, gbase, voff) do { _Pragma("unroll") for (int _i = 0; _i < 2; ++_i) \
;         __builtin_amdgcn_global_load_lds((const unsigned*)((const char*)(gbase) + (voff)[_i]), (LAS unsigned*)(lds + (bufoff) + ldsw + _i * 8192), 16, 0, 0); } while (0)
; #define PG8_LDA(dst, b, h) do { _Pragma("unroll") for (int m = 0; m < NM; ++m) _Pragma("unroll") for (int k = 0; k < 2; ++k) dst[m][k] = *(const LAS bf16x8*)(lds + PG8_SA(b, h) + aoff + m * 2048 + k * 1024); } while (0)
; #define PG8_LDB(dst, b, h) do { _Pragma("unroll") for (int n = 0; n < 2; ++n) _Pragma("unroll") for (int k = 0; k < 2; ++k) dst[n][k] = *(const LAS bf16x8*)(lds + PG8_SB(b, h) + boff + n * 2048 + k * 1024); } while (0)
; #define PG8_SCHED __builtin_amdgcn_sched_barrier(0)
;     ...
;         for (int t = 0; t < nt; t += 2) {
;             const bool last = (t == nt - 2);
;             const char* a1 = cA + (size_t)(t + 1) * kstep;
;             const char* a2 = last ? nA : cA + (size_t)(t + 2) * kstep; const char* b2 = last ? nB : cB + (size_t)(t + 2) * kstep;
;             const char* a3 = a2 + kstep; const char* b3 = b2 + kstep;
;             if constexpr (SP2) {
;             PG8_LDB(B0, 0, 0); PG8_LDB(B1, 0, 1); PG8_SCHED; PG8_LDA(At, 0, 0); PG8_STAGE(PG8_SA(1, 1), a1 + hstepA, voffA);
.LBB0_2158:
	v_add_u32_e32 v102, s26, v166
	v_add_u32_e32 v126, s29, v166
	ds_read_b128 v[90:93], v102
	ds_read_b128 v[94:97], v102 offset:1024
	ds_read_b128 v[98:101], v102 offset:2048
	ds_read_b128 v[102:105], v102 offset:3072
	ds_read_b128 v[114:117], v126
	ds_read_b128 v[118:121], v126 offset:1024
	ds_read_b128 v[122:125], v126 offset:2048
	ds_read_b128 v[126:129], v126 offset:3072
	s_add_u32 s16, s14, 0x100
	s_addc_u32 s17, s15, 0
	s_cmpk_eq_i32 s60, 0x54
	s_cselect_b32 s21, s7, s17
	s_cselect_b32 s20, s6, s16
	s_cselect_b32 s19, s13, s3
	s_cselect_b32 s18, s12, s2
	s_add_i32 m0, s34, 0xc000
	ds_read_b128 v[130:133], v167
	ds_read_b128 v[134:137], v167 offset:1024
	ds_read_b128 v[138:141], v167 offset:2048
	ds_read_b128 v[152:155], v167 offset:3072
	ds_read_b128 v[156:159], v167 offset:4096
	ds_read_b128 v[160:163], v167 offset:5120
	global_load_lds_dwordx4 v148, s[14:15]
	s_add_i32 m0, s34, 0xe000
	s_nop 0
	s_and_b64 vcc, exec, s[8:9]
	s_cbranch_vccz .Lnm3d_skip0
	global_load_lds_dwordx4 v150, s[14:15]
	s_waitcnt vmcnt(8)
	s_branch .Lnm3d_done0

; #define PG8_STAGE(bufoff, gbase, voff) do { _Pragma("unroll") for (int _i = 0; _i < 2; ++_i) \
;         __builtin_amdgcn_global_load_lds((const unsigned*)((const char*)(gbase) + (voff)[_i]), (LAS unsigned*)(lds + (bufoff) + ldsw + _i * 8192), 16, 0, 0); } while (0)
; #define PG8_LDA(dst, b, h) do { _Pragma("unroll") for (int m = 0; m < NM; ++m) _Pragma("unroll") for (int k = 0; k < 2; ++k) dst[m][k] = *(const LAS bf16x8*)(lds + PG8_SA(b, h) + aoff + m * 2048 + k * 1024); } while (0)
; #define PG8_MMA(ai, bj, At, Bt) do { __builtin_amdgcn_s_setprio(1); _Pragma("unroll") for (int m = 0; m < NM; ++m) _Pragma("unroll") for (int n = 0; n < 2; ++n) _Pragma("unroll") for (int k = 0; k < 2; ++k) \
;         acc[ai][bj][m][n] = __builtin_amdgcn_mfma_f32_16x16x32_bf16(Bt[n][k], At[m][k], acc[ai][bj][m][n], 0, 0, 0); __builtin_amdgcn_s_setprio(0); } while (0)
; #define PG8_WAIT_V(n) asm volatile("s_waitcnt vmcnt(" #n ")" ::: "memory")
; #define PG8_WAIT_L(n) asm volatile("s_waitcnt lgkmcnt(" #n ")" ::: "memory")
; #define PG8_BAR __builtin_amdgcn_s_barrier()
; #define PG8_SCHED __builtin_amdgcn_sched_barrier(0)
;     ...
;             PG8_WAIT_V(8); PG8_WAIT_L(0); PG8_BAR; PG8_MMA(0, 0, At, B0); PG8_MMA(0, 1, At, B1); PG8_BAR; PG8_SCHED;
;             PG8_LDA(At, 0, 1); PG8_STAGE(PG8_SB(0, 0), b2, voffB); PG8_STAGE(PG8_SB(0, 1), b2 + hstepB, voffB); PG8_STAGE(PG8_SA(0, 0), a2, voffA);
.Lnm3d_done0:
	s_waitcnt lgkmcnt(0)
	s_barrier
	s_setprio 1
	s_waitcnt lgkmcnt(0)
	v_mfma_f32_16x16x32_bf16 v[110:113], v[90:93], v[130:133], v[110:113]
	v_mfma_f32_16x16x32_bf16 v[106:109], v[98:101], v[130:133], v[106:109]
	v_mfma_f32_16x16x32_bf16 v[78:81], v[90:93], v[138:141], v[78:81]
	v_mfma_f32_16x16x32_bf16 v[74:77], v[98:101], v[138:141], v[74:77]
	v_mfma_f32_16x16x32_bf16 v[62:65], v[90:93], v[156:159], v[62:65]
	v_mfma_f32_16x16x32_bf16 v[58:61], v[98:101], v[156:159], v[58:61]
	v_mfma_f32_16x16x32_bf16 v[110:113], v[94:97], v[134:137], v[110:113]
	v_mfma_f32_16x16x32_bf16 v[106:109], v[102:105], v[134:137], v[106:109]
	v_mfma_f32_16x16x32_bf16 v[78:81], v[94:97], v[152:155], v[78:81]
	v_mfma_f32_16x16x32_bf16 v[74:77], v[102:105], v[152:155], v[74:77]
	v_mfma_f32_16x16x32_bf16 v[62:65], v[94:97], v[160:163], v[62:65]
	v_mfma_f32_16x16x32_bf16 v[58:61], v[102:105], v[160:163], v[58:61]
	s_setprio 0
	s_setprio 1
	v_mfma_f32_16x16x32_bf16 v[86:89], v[114:117], v[130:133], v[86:89]
	v_mfma_f32_16x16x32_bf16 v[82:85], v[122:125], v[130:133], v[82:85]
	v_mfma_f32_16x16x32_bf16 v[70:73], v[114:117], v[138:141], v[70:73]
	v_mfma_f32_16x16x32_bf16 v[66:69], v[122:125], v[138:141], v[66:69]
	v_mfma_f32_16x16x32_bf16 v[54:57], v[114:117], v[156:159], v[54:57]
	v_mfma_f32_16x16x32_bf16 v[50:53], v[122:125], v[156:159], v[50:53]
	v_mfma_f32_16x16x32_bf16 v[86:89], v[118:121], v[134:137], v[86:89]
	v_mfma_f32_16x16x32_bf16 v[82:85], v[126:129], v[134:137], v[82:85]
	v_mfma_f32_16x16x32_bf16 v[70:73], v[118:121], v[152:155], v[70:73]
	v_mfma_f32_16x16x32_bf16 v[66:69], v[126:129], v[152:155], v[66:69]
	v_mfma_f32_16x16x32_bf16 v[54:57], v[118:121], v[160:163], v[54:57]
	v_mfma_f32_16x16x32_bf16 v[50:53], v[126:129], v[160:163], v[50:53]
	s_setprio 0
	s_barrier
	s_mov_b32 m0, s27
	v_lshl_add_u64 v[164:165], s[18:19], 0, v[0:1]
	s_add_u32 s14, s18, 0x160000
	ds_read_b128 v[130:133], v167 offset:16384
	ds_read_b128 v[134:137], v167 offset:17408
	ds_read_b128 v[138:141], v167 offset:18432
	ds_read_b128 v[152:155], v167 offset:19456
	ds_read_b128 v[156:159], v167 offset:20480
	ds_read_b128 v[160:163], v167 offset:21504
	global_load_lds_dwordx4 v0, s[18:19]
	v_lshl_add_u64 v[168:169], s[18:19], 0, v[146:147]
	s_mov_b32 m0, s28
	s_addc_u32 s15, s19, 0
	global_load_lds_dwordx4 v146, s[18:19]
	s_mov_b32 m0, s30
	v_lshl_add_u64 v[172:173], s[20:21], 0, v[144:145]
	global_load_lds_dwordx4 v0, s[14:15]
	s_mov_b32 m0, s31
	s_nop 0
	global_load_lds_dwordx4 v146, s[14:15]
	v_lshl_add_u64 v[170:171], s[20:21], 0, v[142:143]
	s_mov_b32 m0, s34
	s_nop 0
	global_load_lds_dwordx4 v142, s[20:21]
	s_mov_b32 m0, s35
	s_nop 0
	s_and_b64 vcc, exec, s[8:9]
	s_cbranch_vccz .Lnm3d_skip1
	global_load_lds_dwordx4 v144, s[20:21]
	s_waitcnt vmcnt(8)
	s_branch .Lnm3d_done1

; #define PG8_STAGE(bufoff, gbase, voff) do { _Pragma("unroll") for (int _i = 0; _i < 2; ++_i) \
;         __builtin_amdgcn_global_load_lds((const unsigned*)((const char*)(gbase) + (voff)[_i]), (LAS unsigned*)(lds + (bufoff) + ldsw + _i * 8192), 16, 0, 0); } while (0)
; #define PG8_LDA(dst, b, h) do { _Pragma("unroll") for (int m = 0; m < NM; ++m) _Pragma("unroll") for (int k = 0; k < 2; ++k) dst[m][k] = *(const LAS bf16x8*)(lds + PG8_SA(b, h) + aoff + m * 2048 + k * 1024); } while (0)
; #define PG8_LDB(dst, b, h) do { _Pragma("unroll") for (int n = 0; n < 2; ++n) _Pragma("unroll") for (int k = 0; k < 2; ++k) dst[n][k] = *(const LAS bf16x8*)(lds + PG8_SB(b, h) + boff + n * 2048 + k * 1024); } while (0)
; #define PG8_MMA(ai, bj, At, Bt) do { __builtin_amdgcn_s_setprio(1); _Pragma("unroll") for (int m = 0; m < NM; ++m) _Pragma("unroll") for (int n = 0; n < 2; ++n) _Pragma("unroll") for (int k = 0; k < 2; ++k) \
;         acc[ai][bj][m][n] = __builtin_amdgcn_mfma_f32_16x16x32_bf16(Bt[n][k], At[m][k], acc[ai][bj][m][n], 0, 0, 0); __builtin_amdgcn_s_setprio(0); } while (0)
; #define PG8_WAIT_V(n) asm volatile("s_waitcnt vmcnt(" #n ")" ::: "memory")
; #define PG8_WAIT_L(n) asm volatile("s_waitcnt lgkmcnt(" #n ")" ::: "memory")
; #define PG8_BAR __builtin_amdgcn_s_barrier()
; #define PG8_SCHED __builtin_amdgcn_sched_barrier(0)
;     ...
;             PG8_WAIT_V(8); PG8_WAIT_L(0); PG8_BAR; PG8_MMA(1, 0, At, B0); PG8_MMA(1, 1, At, B1); PG8_BAR; PG8_SCHED;
;             PG8_LDB(B0, 1, 0); PG8_LDB(B1, 1, 1); PG8_SCHED; PG8_LDA(At, 1, 0); PG8_STAGE(PG8_SA(0, 1), a2 + hstepA, voffA);
.Lnm3d_done1:
	s_waitcnt lgkmcnt(0)
	s_barrier
	s_setprio 1
	s_waitcnt lgkmcnt(0)
	v_mfma_f32_16x16x32_bf16 v[46:49], v[90:93], v[130:133], v[46:49]
	v_mfma_f32_16x16x32_bf16 v[42:45], v[98:101], v[130:133], v[42:45]
	v_mfma_f32_16x16x32_bf16 v[30:33], v[90:93], v[138:141], v[30:33]
	v_mfma_f32_16x16x32_bf16 v[26:29], v[98:101], v[138:141], v[26:29]
	v_mfma_f32_16x16x32_bf16 v[14:17], v[90:93], v[156:159], v[14:17]
	v_mfma_f32_16x16x32_bf16 v[10:13], v[98:101], v[156:159], v[10:13]
	v_mfma_f32_16x16x32_bf16 v[46:49], v[94:97], v[134:137], v[46:49]
	v_mfma_f32_16x16x32_bf16 v[42:45], v[102:105], v[134:137], v[42:45]
	v_mfma_f32_16x16x32_bf16 v[30:33], v[94:97], v[152:155], v[30:33]
	v_mfma_f32_16x16x32_bf16 v[26:29], v[102:105], v[152:155], v[26:29]
	v_mfma_f32_16x16x32_bf16 v[14:17], v[94:97], v[160:163], v[14:17]
	v_mfma_f32_16x16x32_bf16 v[10:13], v[102:105], v[160:163], v[10:13]
	s_setprio 0
	s_setprio 1
	v_mfma_f32_16x16x32_bf16 v[38:41], v[114:117], v[130:133], v[38:41]
	v_mfma_f32_16x16x32_bf16 v[34:37], v[122:125], v[130:133], v[34:37]
	v_mfma_f32_16x16x32_bf16 v[22:25], v[114:117], v[138:141], v[22:25]
	v_mfma_f32_16x16x32_bf16 v[18:21], v[122:125], v[138:141], v[18:21]
	v_mfma_f32_16x16x32_bf16 v[6:9], v[114:117], v[156:159], v[6:9]
	v_mfma_f32_16x16x32_bf16 v[2:5], v[122:125], v[156:159], v[2:5]
	v_mfma_f32_16x16x32_bf16 v[38:41], v[118:121], v[134:137], v[38:41]
	v_mfma_f32_16x16x32_bf16 v[34:37], v[126:129], v[134:137], v[34:37]
	v_mfma_f32_16x16x32_bf16 v[22:25], v[118:121], v[152:155], v[22:25]
	v_mfma_f32_16x16x32_bf16 v[18:21], v[126:129], v[152:155], v[18:21]
	v_mfma_f32_16x16x32_bf16 v[6:9], v[118:121], v[160:163], v[6:9]
	v_mfma_f32_16x16x32_bf16 v[2:5], v[126:129], v[160:163], v[2:5]
	s_setprio 0
	s_barrier
	v_add_u32_e32 v102, s38, v166
	v_add_u32_e32 v126, s45, v166
	ds_read_b128 v[90:93], v102
	ds_read_b128 v[94:97], v102 offset:1024
	ds_read_b128 v[98:101], v102 offset:2048
	ds_read_b128 v[102:105], v102 offset:3072
	ds_read_b128 v[114:117], v126
	ds_read_b128 v[118:121], v126 offset:1024
	ds_read_b128 v[122:125], v126 offset:2048
	ds_read_b128 v[126:129], v126 offset:3072
	s_add_u32 s14, s20, 0x108000
	s_addc_u32 s15, s21, 0
	s_mov_b32 m0, s36
	ds_read_b128 v[130:133], v167 offset:32768
	ds_read_b128 v[134:137], v167 offset:33792
	ds_read_b128 v[138:141], v167 offset:34816
	ds_read_b128 v[152:155], v167 offset:35840
	ds_read_b128 v[156:159], v167 offset:36864
	ds_read_b128 v[160:163], v167 offset:37888
	global_load_lds_dwordx4 v142, s[14:15]
	s_mov_b32 m0, s37
	s_nop 0
	s_and_b64 vcc, exec, s[8:9]
	s_cbranch_vccz .Lnm3d_skip2
	global_load_lds_dwordx4 v144, s[14:15]
	s_waitcnt vmcnt(8)
	s_branch .Lnm3d_done2

; #define PG8_STAGE(bufoff, gbase, voff) do { _Pragma("unroll") for (int _i = 0; _i < 2; ++_i) \
;         __builtin_amdgcn_global_load_lds((const unsigned*)((const char*)(gbase) + (voff)[_i]), (LAS unsigned*)(lds + (bufoff) + ldsw + _i * 8192), 16, 0, 0); } while (0)
; #define PG8_LDA(dst, b, h) do { _Pragma("unroll") for (int m = 0; m < NM; ++m) _Pragma("unroll") for (int k = 0; k < 2; ++k) dst[m][k] = *(const LAS bf16x8*)(lds + PG8_SA(b, h) + aoff + m * 2048 + k * 1024); } while (0)
; #define PG8_MMA(ai, bj, At, Bt) do { __builtin_amdgcn_s_setprio(1); _Pragma("unroll") for (int m = 0; m < NM; ++m) _Pragma("unroll") for (int n = 0; n < 2; ++n) _Pragma("unroll") for (int k = 0; k < 2; ++k) \
;         acc[ai][bj][m][n] = __builtin_amdgcn_mfma_f32_16x16x32_bf16(Bt[n][k], At[m][k], acc[ai][bj][m][n], 0, 0, 0); __builtin_amdgcn_s_setprio(0); } while (0)
; #define PG8_WAIT_V(n) asm volatile("s_waitcnt vmcnt(" #n ")" ::: "memory")
; #define PG8_WAIT_L(n) asm volatile("s_waitcnt lgkmcnt(" #n ")" ::: "memory")
; #define PG8_BAR __builtin_amdgcn_s_barrier()
; #define PG8_SCHED __builtin_amdgcn_sched_barrier(0)
;     ...
;             PG8_WAIT_V(8); PG8_WAIT_L(0); PG8_BAR; PG8_MMA(0, 0, At, B0); PG8_MMA(0, 1, At, B1); PG8_BAR; PG8_SCHED;
;             PG8_LDA(At, 1, 1); PG8_STAGE(PG8_SB(1, 0), b3, voffB); PG8_STAGE(PG8_SB(1, 1), b3 + hstepB, voffB); PG8_STAGE(PG8_SA(1, 0), a3, voffA);
.Lnm3d_done2:
	s_waitcnt lgkmcnt(0)
	s_barrier
	s_setprio 1
	s_waitcnt lgkmcnt(0)
	v_mfma_f32_16x16x32_bf16 v[110:113], v[90:93], v[130:133], v[110:113]
	v_mfma_f32_16x16x32_bf16 v[106:109], v[98:101], v[130:133], v[106:109]
	v_mfma_f32_16x16x32_bf16 v[78:81], v[90:93], v[138:141], v[78:81]
	v_mfma_f32_16x16x32_bf16 v[74:77], v[98:101], v[138:141], v[74:77]
	v_mfma_f32_16x16x32_bf16 v[62:65], v[90:93], v[156:159], v[62:65]
	v_mfma_f32_16x16x32_bf16 v[58:61], v[98:101], v[156:159], v[58:61]
	v_mfma_f32_16x16x32_bf16 v[110:113], v[94:97], v[134:137], v[110:113]
	v_mfma_f32_16x16x32_bf16 v[106:109], v[102:105], v[134:137], v[106:109]
	v_mfma_f32_16x16x32_bf16 v[78:81], v[94:97], v[152:155], v[78:81]
	v_mfma_f32_16x16x32_bf16 v[74:77], v[102:105], v[152:155], v[74:77]
	v_mfma_f32_16x16x32_bf16 v[62:65], v[94:97], v[160:163], v[62:65]
	v_mfma_f32_16x16x32_bf16 v[58:61], v[102:105], v[160:163], v[58:61]
	s_setprio 0
	s_setprio 1
	v_mfma_f32_16x16x32_bf16 v[86:89], v[114:117], v[130:133], v[86:89]
	v_mfma_f32_16x16x32_bf16 v[82:85], v[122:125], v[130:133], v[82:85]
	v_mfma_f32_16x16x32_bf16 v[70:73], v[114:117], v[138:141], v[70:73]
	v_mfma_f32_16x16x32_bf16 v[66:69], v[122:125], v[138:141], v[66:69]
	v_mfma_f32_16x16x32_bf16 v[54:57], v[114:117], v[156:159], v[54:57]
	v_mfma_f32_16x16x32_bf16 v[50:53], v[122:125], v[156:159], v[50:53]
	v_mfma_f32_16x16x32_bf16 v[86:89], v[118:121], v[134:137], v[86:89]
	v_mfma_f32_16x16x32_bf16 v[82:85], v[126:129], v[134:137], v[82:85]
	v_mfma_f32_16x16x32_bf16 v[70:73], v[118:121], v[152:155], v[70:73]
	v_mfma_f32_16x16x32_bf16 v[66:69], v[126:129], v[152:155], v[66:69]
	v_mfma_f32_16x16x32_bf16 v[54:57], v[118:121], v[160:163], v[54:57]
	v_mfma_f32_16x16x32_bf16 v[50:53], v[126:129], v[160:163], v[50:53]
	s_setprio 0
	s_barrier
	s_mov_b32 m0, s41
	v_lshl_add_u64 v[164:165], v[164:165], 0, s[66:67]
	s_add_u32 s14, s18, 0x160080
	ds_read_b128 v[130:133], v167 offset:49152
	ds_read_b128 v[134:137], v167 offset:50176
	ds_read_b128 v[138:141], v167 offset:51200
	ds_read_b128 v[152:155], v167 offset:52224
	ds_read_b128 v[156:159], v167 offset:53248
	ds_read_b128 v[160:163], v167 offset:54272
	global_load_lds_dwordx4 v[164:165], off
	v_lshl_add_u64 v[164:165], v[168:169], 0, s[66:67]
	s_mov_b32 m0, s42
	s_addc_u32 s15, s19, 0
	global_load_lds_dwordx4 v[164:165], off
	s_mov_b32 m0, s46
	s_nop 0
	global_load_lds_dwordx4 v0, s[14:15]
	s_mov_b32 m0, s47
	s_nop 0
	global_load_lds_dwordx4 v146, s[14:15]
	v_lshl_add_u64 v[164:165], v[170:171], 0, s[66:67]
	s_mov_b32 m0, s43
	s_nop 0
	global_load_lds_dwordx4 v[164:165], off
	v_lshl_add_u64 v[164:165], v[172:173], 0, s[66:67]
	s_mov_b32 m0, s44
	s_nop 0
	s_and_b64 vcc, exec, s[8:9]
	s_cbranch_vccz .Lnm3d_skip3
	global_load_lds_dwordx4 v[164:165], off
	s_waitcnt vmcnt(8)
	s_branch .Lnm3d_done3
